# P15: exact counted vmcnt wait per pass for the fourth token group (lever 1: counted waits)
# speedup vs baseline: 1.0019x; 1.0019x over previous
; DEV void phase_p15(const Params& p, int g) {
;     ...
; #pragma unroll
;     for (int j8 = 0; j8 < 8; ++j8) {
;       const int st = j8 % 3;
;       if (j8 < 6) { P15_LOAD((j8 + 2) % 3, j8 + 2); }
.Lp15_d0_nl2:
	s_cmp_eq_u32 s35, 0
	s_cbranch_scc1 .Lp15_w32_0
	s_waitcnt vmcnt(16)
	s_branch .Lp15_wd_0

; DEV u16 f2bf(float f) { return (u16)(pack2(f, f) & 0xffffu); }
; DEV float bf2f(u16 h) { return __uint_as_float(((unsigned)h) << 16); }
; DEV float sigmoid_f(float x) { return __builtin_amdgcn_rcpf(1.f + __expf(-x)); }
; DEV void phase_p15(const Params& p, int g) {
;     ...
; #pragma unroll
;       for (int cc = 0; cc < 2; ++cc) {
;         const int c = tid + 256 * cc;
;         unsigned kb[8];
; #pragma unroll
;         for (int e = 0; e < 8; ++e) {
;           const int jj = j8 * 8 + e;
;           const int j = dir ? 63 - jj : jj;
;           const size_t tok = (size_t)cidx * 64 + j;
;           const float f = lb[cc] + (1.f - lb[cc]) * sigmoid_f(bf2f(xr[st][cc][e]));
;           G[cc] += __logf(f);
;           const float eg = __expf(G[cc]), ig = __expf(-G[cc]);
;           Qp[tok * 512 + c] = f2bf(bf2f(qr[st][cc][e]) * eg);
;           const u16 kk = f2bf((1.f - f) * ig);
;           Kp[tok * 512 + c] = kk;
;           kb[e] = kk;
;         }
;         const int s0 = dir ? 56 - 8 * j8 : 8 * j8;
;         uint4 w;
;         w.x = dir ? (kb[7] | (kb[6] << 16)) : (kb[0] | (kb[1] << 16));
;         w.y = dir ? (kb[5] | (kb[4] << 16)) : (kb[2] | (kb[3] << 16));
;         w.z = dir ? (kb[3] | (kb[2] << 16)) : (kb[4] | (kb[5] << 16));
;         w.w = dir ? (kb[1] | (kb[0] << 16)) : (kb[6] | (kb[7] << 16));
;         *(uint4*)(KT + (((size_t)cidx * 2 + dir) * 512 + c) * 64 + s0) = w;
;       }
.Lp15_wd_0:
	v_lshlrev_b32_e32 v92, 16, v32
	v_and_b32_e32 v93, 0xffff0000, v32
	v_lshlrev_b32_e32 v94, 16, v33
	v_and_b32_e32 v95, 0xffff0000, v33
	v_mul_f32_e32 v92, 0xbfb8aa3b, v92
	v_mul_f32_e32 v93, 0xbfb8aa3b, v93
	v_mul_f32_e32 v94, 0xbfb8aa3b, v94
	v_mul_f32_e32 v95, 0xbfb8aa3b, v95
	v_exp_f32_e32 v92, v92
	v_exp_f32_e32 v93, v93
	v_exp_f32_e32 v94, v94
	v_exp_f32_e32 v95, v95
	v_add_f32_e32 v92, 1.0, v92
	v_add_f32_e32 v93, 1.0, v93
	v_add_f32_e32 v94, 1.0, v94
	v_add_f32_e32 v95, 1.0, v95
	v_rcp_f32_e32 v92, v92
	v_rcp_f32_e32 v93, v93
	v_rcp_f32_e32 v94, v94
	v_rcp_f32_e32 v95, v95
	v_fma_f32 v96, v72, v92, v68
	v_fma_f32 v97, v73, v93, v69
	v_fma_f32 v98, v74, v94, v70
	v_fma_f32 v99, v75, v95, v71
	v_cmp_gt_f32_e64 s[22:23], s30, v96
	v_cmp_gt_f32_e64 s[24:25], s30, v97
	v_cmp_gt_f32_e64 s[26:27], s30, v98
	v_cmp_gt_f32_e64 s[28:29], s30, v99
	v_cndmask_b32_e64 v92, 0, 32, s[22:23]
	v_cndmask_b32_e64 v93, 0, 32, s[24:25]
	v_cndmask_b32_e64 v94, 0, 32, s[26:27]
	v_cndmask_b32_e64 v95, 0, 32, s[28:29]
	v_ldexp_f32 v92, v96, v92
	v_ldexp_f32 v93, v97, v93
	v_ldexp_f32 v94, v98, v94
	v_ldexp_f32 v95, v99, v95
	v_log_f32_e32 v92, v92
	v_log_f32_e32 v93, v93
	v_log_f32_e32 v94, v94
	v_log_f32_e32 v95, v95
	v_mul_f32_e32 v100, 0x3f317217, v92
	v_mul_f32_e32 v101, 0x3f317217, v93
	v_mul_f32_e32 v102, 0x3f317217, v94
	v_mul_f32_e32 v103, 0x3f317217, v95
	v_fma_f32 v100, v92, s31, -v100
	v_fma_f32 v101, v93, s31, -v101
	v_fma_f32 v102, v94, s31, -v102
	v_fma_f32 v103, v95, s31, -v103
	v_fmac_f32_e32 v100, 0x3377d1cf, v92
	v_fmac_f32_e32 v101, 0x3377d1cf, v93
	v_fmac_f32_e32 v102, 0x3377d1cf, v94
	v_fmac_f32_e32 v103, 0x3377d1cf, v95
	v_fmac_f32_e32 v100, 0x3f317217, v92
	v_fmac_f32_e32 v101, 0x3f317217, v93
	v_fmac_f32_e32 v102, 0x3f317217, v94
	v_fmac_f32_e32 v103, 0x3f317217, v95
	v_cmp_lt_f32_e64 vcc, |v92|, s34
	v_cndmask_b32_e32 v92, v92, v100, vcc
	v_cmp_lt_f32_e64 vcc, |v93|, s34
	v_cndmask_b32_e32 v93, v93, v101, vcc
	v_cmp_lt_f32_e64 vcc, |v94|, s34
	v_cndmask_b32_e32 v94, v94, v102, vcc
	v_cmp_lt_f32_e64 vcc, |v95|, s34
	v_cndmask_b32_e32 v95, v95, v103, vcc
	v_cndmask_b32_e64 v100, 0, v213, s[22:23]
	v_cndmask_b32_e64 v101, 0, v213, s[24:25]
	v_cndmask_b32_e64 v102, 0, v213, s[26:27]
	v_cndmask_b32_e64 v103, 0, v213, s[28:29]
	v_sub_f32_e32 v92, v92, v100
	v_sub_f32_e32 v93, v93, v101
	v_sub_f32_e32 v94, v94, v102
	v_sub_f32_e32 v95, v95, v103
	v_add_f32_e32 v64, v64, v92
	v_add_f32_e32 v65, v65, v93
	v_add_f32_e32 v66, v66, v94
	v_add_f32_e32 v67, v67, v95
	v_mul_f32_e32 v92, 0xbfb8aa3b, v64
	v_mul_f32_e32 v93, 0xbfb8aa3b, v65
	v_mul_f32_e32 v94, 0xbfb8aa3b, v66
	v_mul_f32_e32 v95, 0xbfb8aa3b, v67
	v_mul_f32_e32 v100, 0x3fb8aa3b, v64
	v_mul_f32_e32 v101, 0x3fb8aa3b, v65
	v_mul_f32_e32 v102, 0x3fb8aa3b, v66
	v_mul_f32_e32 v103, 0x3fb8aa3b, v67
	v_exp_f32_e32 v92, v92
	v_exp_f32_e32 v93, v93
	v_exp_f32_e32 v94, v94
	v_exp_f32_e32 v95, v95
	v_exp_f32_e32 v100, v100
	v_exp_f32_e32 v101, v101
	v_exp_f32_e32 v102, v102
	v_exp_f32_e32 v103, v103
	v_sub_f32_e32 v96, 1.0, v96
	v_sub_f32_e32 v97, 1.0, v97
	v_sub_f32_e32 v98, 1.0, v98
	v_sub_f32_e32 v99, 1.0, v99
	v_mul_f32_e32 v96, v96, v92
	v_mul_f32_e32 v97, v97, v93
	v_mul_f32_e32 v98, v98, v94
	v_mul_f32_e32 v99, v99, v95
	v_lshlrev_b32_e32 v92, 16, v34
	v_and_b32_e32 v93, 0xffff0000, v34
	v_lshlrev_b32_e32 v94, 16, v35
	v_and_b32_e32 v95, 0xffff0000, v35
	v_mul_f32_e32 v92, v92, v100
	v_mul_f32_e32 v93, v93, v101
	v_mul_f32_e32 v94, v94, v102
	v_mul_f32_e32 v95, v95, v103
	v_mov_b32_e32 v128, v96
	v_mov_b32_e32 v144, v97
	v_mov_b32_e32 v178, v98
	v_mov_b32_e32 v194, v99
	v_cvt_pk_bf16_f32 v92, v92, v93
	v_cvt_pk_bf16_f32 v93, v94, v95
	v_cvt_pk_bf16_f32 v96, v96, v97
	v_cvt_pk_bf16_f32 v97, v98, v99
	global_store_dwordx2 v112, v[92:93], s[2:3]
	global_store_dwordx2 v114, v[96:97], s[2:3]
	s_add_u32 s2, s2, 0x400
	s_addc_u32 s3, s3, 0
	v_lshlrev_b32_e32 v92, 16, v36
	v_and_b32_e32 v93, 0xffff0000, v36
	v_lshlrev_b32_e32 v94, 16, v37
	v_and_b32_e32 v95, 0xffff0000, v37
	v_mul_f32_e32 v92, 0xbfb8aa3b, v92
	v_mul_f32_e32 v93, 0xbfb8aa3b, v93
	v_mul_f32_e32 v94, 0xbfb8aa3b, v94
	v_mul_f32_e32 v95, 0xbfb8aa3b, v95
	v_exp_f32_e32 v92, v92
	v_exp_f32_e32 v93, v93
	v_exp_f32_e32 v94, v94
	v_exp_f32_e32 v95, v95
	v_add_f32_e32 v92, 1.0, v92
	v_add_f32_e32 v93, 1.0, v93
	v_add_f32_e32 v94, 1.0, v94
	v_add_f32_e32 v95, 1.0, v95
	v_rcp_f32_e32 v92, v92
	v_rcp_f32_e32 v93, v93
	v_rcp_f32_e32 v94, v94
	v_rcp_f32_e32 v95, v95
	v_fma_f32 v96, v72, v92, v68
	v_fma_f32 v97, v73, v93, v69
	v_fma_f32 v98, v74, v94, v70
	v_fma_f32 v99, v75, v95, v71
	v_cmp_gt_f32_e64 s[22:23], s30, v96
	v_cmp_gt_f32_e64 s[24:25], s30, v97
	v_cmp_gt_f32_e64 s[26:27], s30, v98
	v_cmp_gt_f32_e64 s[28:29], s30, v99
	v_cndmask_b32_e64 v92, 0, 32, s[22:23]
	v_cndmask_b32_e64 v93, 0, 32, s[24:25]
	v_cndmask_b32_e64 v94, 0, 32, s[26:27]
	v_cndmask_b32_e64 v95, 0, 32, s[28:29]
	v_ldexp_f32 v92, v96, v92
	v_ldexp_f32 v93, v97, v93
	v_ldexp_f32 v94, v98, v94
	v_ldexp_f32 v95, v99, v95
	v_log_f32_e32 v92, v92
	v_log_f32_e32 v93, v93
	v_log_f32_e32 v94, v94
	v_log_f32_e32 v95, v95
	v_mul_f32_e32 v100, 0x3f317217, v92
	v_mul_f32_e32 v101, 0x3f317217, v93
	v_mul_f32_e32 v102, 0x3f317217, v94
	v_mul_f32_e32 v103, 0x3f317217, v95
	v_fma_f32 v100, v92, s31, -v100
	v_fma_f32 v101, v93, s31, -v101
	v_fma_f32 v102, v94, s31, -v102
	v_fma_f32 v103, v95, s31, -v103
	v_fmac_f32_e32 v100, 0x3377d1cf, v92
	v_fmac_f32_e32 v101, 0x3377d1cf, v93
	v_fmac_f32_e32 v102, 0x3377d1cf, v94
	v_fmac_f32_e32 v103, 0x3377d1cf, v95
	v_fmac_f32_e32 v100, 0x3f317217, v92
	v_fmac_f32_e32 v101, 0x3f317217, v93
	v_fmac_f32_e32 v102, 0x3f317217, v94
; DEV u16 f2bf(float f) { return (u16)(pack2(f, f) & 0xffffu); }
; DEV float bf2f(u16 h) { return __uint_as_float(((unsigned)h) << 16); }
; DEV float sigmoid_f(float x) { return __builtin_amdgcn_rcpf(1.f + __expf(-x)); }
; DEV void phase_p15(const Params& p, int g) {
;     ...
; #pragma unroll
;       for (int cc = 0; cc < 2; ++cc) {
;         const int c = tid + 256 * cc;
;         unsigned kb[8];
; #pragma unroll
;         for (int e = 0; e < 8; ++e) {
;           const int jj = j8 * 8 + e;
;           const int j = dir ? 63 - jj : jj;
;           const size_t tok = (size_t)cidx * 64 + j;
;           const float f = lb[cc] + (1.f - lb[cc]) * sigmoid_f(bf2f(xr[st][cc][e]));
;           G[cc] += __logf(f);
;           const float eg = __expf(G[cc]), ig = __expf(-G[cc]);
;           Qp[tok * 512 + c] = f2bf(bf2f(qr[st][cc][e]) * eg);
;           const u16 kk = f2bf((1.f - f) * ig);
;           Kp[tok * 512 + c] = kk;
;           kb[e] = kk;
;         }
;         const int s0 = dir ? 56 - 8 * j8 : 8 * j8;
;         uint4 w;
;         w.x = dir ? (kb[7] | (kb[6] << 16)) : (kb[0] | (kb[1] << 16));
;         w.y = dir ? (kb[5] | (kb[4] << 16)) : (kb[2] | (kb[3] << 16));
;         w.z = dir ? (kb[3] | (kb[2] << 16)) : (kb[4] | (kb[5] << 16));
;         w.w = dir ? (kb[1] | (kb[0] << 16)) : (kb[6] | (kb[7] << 16));
;         *(uint4*)(KT + (((size_t)cidx * 2 + dir) * 512 + c) * 64 + s0) = w;
;       }
	v_fmac_f32_e32 v103, 0x3f317217, v95
	v_cmp_lt_f32_e64 vcc, |v92|, s34
	v_cndmask_b32_e32 v92, v92, v100, vcc
	v_cmp_lt_f32_e64 vcc, |v93|, s34
	v_cndmask_b32_e32 v93, v93, v101, vcc
	v_cmp_lt_f32_e64 vcc, |v94|, s34
	v_cndmask_b32_e32 v94, v94, v102, vcc
	v_cmp_lt_f32_e64 vcc, |v95|, s34
	v_cndmask_b32_e32 v95, v95, v103, vcc
	v_cndmask_b32_e64 v100, 0, v213, s[22:23]
	v_cndmask_b32_e64 v101, 0, v213, s[24:25]
	v_cndmask_b32_e64 v102, 0, v213, s[26:27]
	v_cndmask_b32_e64 v103, 0, v213, s[28:29]
	v_sub_f32_e32 v92, v92, v100
	v_sub_f32_e32 v93, v93, v101
	v_sub_f32_e32 v94, v94, v102
	v_sub_f32_e32 v95, v95, v103
	v_add_f32_e32 v64, v64, v92
	v_add_f32_e32 v65, v65, v93
	v_add_f32_e32 v66, v66, v94
	v_add_f32_e32 v67, v67, v95
	v_mul_f32_e32 v92, 0xbfb8aa3b, v64
	v_mul_f32_e32 v93, 0xbfb8aa3b, v65
	v_mul_f32_e32 v94, 0xbfb8aa3b, v66
	v_mul_f32_e32 v95, 0xbfb8aa3b, v67
	v_mul_f32_e32 v100, 0x3fb8aa3b, v64
	v_mul_f32_e32 v101, 0x3fb8aa3b, v65
	v_mul_f32_e32 v102, 0x3fb8aa3b, v66
	v_mul_f32_e32 v103, 0x3fb8aa3b, v67
	v_exp_f32_e32 v92, v92
	v_exp_f32_e32 v93, v93
	v_exp_f32_e32 v94, v94
	v_exp_f32_e32 v95, v95
	v_exp_f32_e32 v100, v100
	v_exp_f32_e32 v101, v101
	v_exp_f32_e32 v102, v102
	v_exp_f32_e32 v103, v103
	v_sub_f32_e32 v96, 1.0, v96
	v_sub_f32_e32 v97, 1.0, v97
	v_sub_f32_e32 v98, 1.0, v98
	v_sub_f32_e32 v99, 1.0, v99
	v_mul_f32_e32 v96, v96, v92
	v_mul_f32_e32 v97, v97, v93
	v_mul_f32_e32 v98, v98, v94
	v_mul_f32_e32 v99, v99, v95
	v_lshlrev_b32_e32 v92, 16, v38
	v_and_b32_e32 v93, 0xffff0000, v38
	v_lshlrev_b32_e32 v94, 16, v39
	v_and_b32_e32 v95, 0xffff0000, v39
	v_mul_f32_e32 v92, v92, v100
	v_mul_f32_e32 v93, v93, v101
	v_mul_f32_e32 v94, v94, v102
	v_mul_f32_e32 v95, v95, v103
	v_cvt_pk_bf16_f32 v128, v128, v96
	v_cvt_pk_bf16_f32 v144, v144, v97
	v_cvt_pk_bf16_f32 v178, v178, v98
	v_cvt_pk_bf16_f32 v194, v194, v99
	v_cvt_pk_bf16_f32 v92, v92, v93
	v_cvt_pk_bf16_f32 v93, v94, v95
	v_cvt_pk_bf16_f32 v96, v96, v97
	v_cvt_pk_bf16_f32 v97, v98, v99
	global_store_dwordx2 v112, v[92:93], s[2:3]
	global_store_dwordx2 v114, v[96:97], s[2:3]
	s_add_u32 s2, s2, 0x400
	s_addc_u32 s3, s3, 0
	v_lshlrev_b32_e32 v92, 16, v40
	v_and_b32_e32 v93, 0xffff0000, v40
	v_lshlrev_b32_e32 v94, 16, v41
	v_and_b32_e32 v95, 0xffff0000, v41
	v_mul_f32_e32 v92, 0xbfb8aa3b, v92
	v_mul_f32_e32 v93, 0xbfb8aa3b, v93
	v_mul_f32_e32 v94, 0xbfb8aa3b, v94
	v_mul_f32_e32 v95, 0xbfb8aa3b, v95
	v_exp_f32_e32 v92, v92
	v_exp_f32_e32 v93, v93
	v_exp_f32_e32 v94, v94
	v_exp_f32_e32 v95, v95
	v_add_f32_e32 v92, 1.0, v92
	v_add_f32_e32 v93, 1.0, v93
	v_add_f32_e32 v94, 1.0, v94
	v_add_f32_e32 v95, 1.0, v95
	v_rcp_f32_e32 v92, v92
	v_rcp_f32_e32 v93, v93
	v_rcp_f32_e32 v94, v94
	v_rcp_f32_e32 v95, v95
	v_fma_f32 v96, v72, v92, v68
	v_fma_f32 v97, v73, v93, v69
	v_fma_f32 v98, v74, v94, v70
	v_fma_f32 v99, v75, v95, v71
	v_cmp_gt_f32_e64 s[22:23], s30, v96
	v_cmp_gt_f32_e64 s[24:25], s30, v97
	v_cmp_gt_f32_e64 s[26:27], s30, v98
	v_cmp_gt_f32_e64 s[28:29], s30, v99
	v_cndmask_b32_e64 v92, 0, 32, s[22:23]
	v_cndmask_b32_e64 v93, 0, 32, s[24:25]
	v_cndmask_b32_e64 v94, 0, 32, s[26:27]
	v_cndmask_b32_e64 v95, 0, 32, s[28:29]
	v_ldexp_f32 v92, v96, v92
	v_ldexp_f32 v93, v97, v93
	v_ldexp_f32 v94, v98, v94
	v_ldexp_f32 v95, v99, v95
	v_log_f32_e32 v92, v92
	v_log_f32_e32 v93, v93
	v_log_f32_e32 v94, v94
	v_log_f32_e32 v95, v95
	v_mul_f32_e32 v100, 0x3f317217, v92
	v_mul_f32_e32 v101, 0x3f317217, v93
	v_mul_f32_e32 v102, 0x3f317217, v94
	v_mul_f32_e32 v103, 0x3f317217, v95
	v_fma_f32 v100, v92, s31, -v100
	v_fma_f32 v101, v93, s31, -v101
	v_fma_f32 v102, v94, s31, -v102
	v_fma_f32 v103, v95, s31, -v103
	v_fmac_f32_e32 v100, 0x3377d1cf, v92
	v_fmac_f32_e32 v101, 0x3377d1cf, v93
	v_fmac_f32_e32 v102, 0x3377d1cf, v94
	v_fmac_f32_e32 v103, 0x3377d1cf, v95
	v_fmac_f32_e32 v100, 0x3f317217, v92
	v_fmac_f32_e32 v101, 0x3f317217, v93
	v_fmac_f32_e32 v102, 0x3f317217, v94
	v_fmac_f32_e32 v103, 0x3f317217, v95
	v_cmp_lt_f32_e64 vcc, |v92|, s34
	v_cndmask_b32_e32 v92, v92, v100, vcc
	v_cmp_lt_f32_e64 vcc, |v93|, s34
	v_cndmask_b32_e32 v93, v93, v101, vcc
	v_cmp_lt_f32_e64 vcc, |v94|, s34
	v_cndmask_b32_e32 v94, v94, v102, vcc
	v_cmp_lt_f32_e64 vcc, |v95|, s34
	v_cndmask_b32_e32 v95, v95, v103, vcc
	v_cndmask_b32_e64 v100, 0, v213, s[22:23]
	v_cndmask_b32_e64 v101, 0, v213, s[24:25]
	v_cndmask_b32_e64 v102, 0, v213, s[26:27]
	v_cndmask_b32_e64 v103, 0, v213, s[28:29]
	v_sub_f32_e32 v92, v92, v100
	v_sub_f32_e32 v93, v93, v101
	v_sub_f32_e32 v94, v94, v102
	v_sub_f32_e32 v95, v95, v103
	v_add_f32_e32 v64, v64, v92
	v_add_f32_e32 v65, v65, v93
	v_add_f32_e32 v66, v66, v94
	v_add_f32_e32 v67, v67, v95
	v_mul_f32_e32 v92, 0xbfb8aa3b, v64
	v_mul_f32_e32 v93, 0xbfb8aa3b, v65
	v_mul_f32_e32 v94, 0xbfb8aa3b, v66
	v_mul_f32_e32 v95, 0xbfb8aa3b, v67
	v_mul_f32_e32 v100, 0x3fb8aa3b, v64
	v_mul_f32_e32 v101, 0x3fb8aa3b, v65
	v_mul_f32_e32 v102, 0x3fb8aa3b, v66
	v_mul_f32_e32 v103, 0x3fb8aa3b, v67
	v_exp_f32_e32 v92, v92
	v_exp_f32_e32 v93, v93
	v_exp_f32_e32 v94, v94
	v_exp_f32_e32 v95, v95
	v_exp_f32_e32 v100, v100
	v_exp_f32_e32 v101, v101
	v_exp_f32_e32 v102, v102
	v_exp_f32_e32 v103, v103
	v_sub_f32_e32 v96, 1.0, v96
	v_sub_f32_e32 v97, 1.0, v97
	v_sub_f32_e32 v98, 1.0, v98
	v_sub_f32_e32 v99, 1.0, v99
	v_mul_f32_e32 v96, v96, v92
	v_mul_f32_e32 v97, v97, v93
	v_mul_f32_e32 v98, v98, v94
	v_mul_f32_e32 v99, v99, v95
	v_lshlrev_b32_e32 v92, 16, v42
	v_and_b32_e32 v93, 0xffff0000, v42
	v_lshlrev_b32_e32 v94, 16, v43
	v_and_b32_e32 v95, 0xffff0000, v43
	v_mul_f32_e32 v92, v92, v100
	v_mul_f32_e32 v93, v93, v101
	v_mul_f32_e32 v94, v94, v102
	v_mul_f32_e32 v95, v95, v103
	v_mov_b32_e32 v129, v96
; DEV u16 f2bf(float f) { return (u16)(pack2(f, f) & 0xffffu); }
; DEV float bf2f(u16 h) { return __uint_as_float(((unsigned)h) << 16); }
; DEV float sigmoid_f(float x) { return __builtin_amdgcn_rcpf(1.f + __expf(-x)); }
; DEV void phase_p15(const Params& p, int g) {
;     ...
; #pragma unroll
;       for (int cc = 0; cc < 2; ++cc) {
;         const int c = tid + 256 * cc;
;         unsigned kb[8];
; #pragma unroll
;         for (int e = 0; e < 8; ++e) {
;           const int jj = j8 * 8 + e;
;           const int j = dir ? 63 - jj : jj;
;           const size_t tok = (size_t)cidx * 64 + j;
;           const float f = lb[cc] + (1.f - lb[cc]) * sigmoid_f(bf2f(xr[st][cc][e]));
;           G[cc] += __logf(f);
;           const float eg = __expf(G[cc]), ig = __expf(-G[cc]);
;           Qp[tok * 512 + c] = f2bf(bf2f(qr[st][cc][e]) * eg);
;           const u16 kk = f2bf((1.f - f) * ig);
;           Kp[tok * 512 + c] = kk;
;           kb[e] = kk;
;         }
;         const int s0 = dir ? 56 - 8 * j8 : 8 * j8;
;         uint4 w;
;         w.x = dir ? (kb[7] | (kb[6] << 16)) : (kb[0] | (kb[1] << 16));
;         w.y = dir ? (kb[5] | (kb[4] << 16)) : (kb[2] | (kb[3] << 16));
;         w.z = dir ? (kb[3] | (kb[2] << 16)) : (kb[4] | (kb[5] << 16));
;         w.w = dir ? (kb[1] | (kb[0] << 16)) : (kb[6] | (kb[7] << 16));
;         *(uint4*)(KT + (((size_t)cidx * 2 + dir) * 512 + c) * 64 + s0) = w;
;       }
	v_mov_b32_e32 v145, v97
	v_mov_b32_e32 v179, v98
	v_mov_b32_e32 v195, v99
	v_cvt_pk_bf16_f32 v92, v92, v93
	v_cvt_pk_bf16_f32 v93, v94, v95
	v_cvt_pk_bf16_f32 v96, v96, v97
	v_cvt_pk_bf16_f32 v97, v98, v99
	global_store_dwordx2 v112, v[92:93], s[2:3]
	global_store_dwordx2 v114, v[96:97], s[2:3]
	s_add_u32 s2, s2, 0x400
	s_addc_u32 s3, s3, 0
	v_lshlrev_b32_e32 v92, 16, v44
	v_and_b32_e32 v93, 0xffff0000, v44
	v_lshlrev_b32_e32 v94, 16, v45
	v_and_b32_e32 v95, 0xffff0000, v45
	v_mul_f32_e32 v92, 0xbfb8aa3b, v92
	v_mul_f32_e32 v93, 0xbfb8aa3b, v93
	v_mul_f32_e32 v94, 0xbfb8aa3b, v94
	v_mul_f32_e32 v95, 0xbfb8aa3b, v95
	v_exp_f32_e32 v92, v92
	v_exp_f32_e32 v93, v93
	v_exp_f32_e32 v94, v94
	v_exp_f32_e32 v95, v95
	v_add_f32_e32 v92, 1.0, v92
	v_add_f32_e32 v93, 1.0, v93
	v_add_f32_e32 v94, 1.0, v94
	v_add_f32_e32 v95, 1.0, v95
	v_rcp_f32_e32 v92, v92
	v_rcp_f32_e32 v93, v93
	v_rcp_f32_e32 v94, v94
	v_rcp_f32_e32 v95, v95
	v_fma_f32 v96, v72, v92, v68
	v_fma_f32 v97, v73, v93, v69
	v_fma_f32 v98, v74, v94, v70
	v_fma_f32 v99, v75, v95, v71
	v_cmp_gt_f32_e64 s[22:23], s30, v96
	v_cmp_gt_f32_e64 s[24:25], s30, v97
	v_cmp_gt_f32_e64 s[26:27], s30, v98
	v_cmp_gt_f32_e64 s[28:29], s30, v99
	v_cndmask_b32_e64 v92, 0, 32, s[22:23]
	v_cndmask_b32_e64 v93, 0, 32, s[24:25]
	v_cndmask_b32_e64 v94, 0, 32, s[26:27]
	v_cndmask_b32_e64 v95, 0, 32, s[28:29]
	v_ldexp_f32 v92, v96, v92
	v_ldexp_f32 v93, v97, v93
	v_ldexp_f32 v94, v98, v94
	v_ldexp_f32 v95, v99, v95
	v_log_f32_e32 v92, v92
	v_log_f32_e32 v93, v93
	v_log_f32_e32 v94, v94
	v_log_f32_e32 v95, v95
	v_mul_f32_e32 v100, 0x3f317217, v92
	v_mul_f32_e32 v101, 0x3f317217, v93
	v_mul_f32_e32 v102, 0x3f317217, v94
	v_mul_f32_e32 v103, 0x3f317217, v95
	v_fma_f32 v100, v92, s31, -v100
	v_fma_f32 v101, v93, s31, -v101
	v_fma_f32 v102, v94, s31, -v102
	v_fma_f32 v103, v95, s31, -v103
	v_fmac_f32_e32 v100, 0x3377d1cf, v92
	v_fmac_f32_e32 v101, 0x3377d1cf, v93
	v_fmac_f32_e32 v102, 0x3377d1cf, v94
	v_fmac_f32_e32 v103, 0x3377d1cf, v95
	v_fmac_f32_e32 v100, 0x3f317217, v92
	v_fmac_f32_e32 v101, 0x3f317217, v93
	v_fmac_f32_e32 v102, 0x3f317217, v94
	v_fmac_f32_e32 v103, 0x3f317217, v95
	v_cmp_lt_f32_e64 vcc, |v92|, s34
	v_cndmask_b32_e32 v92, v92, v100, vcc
	v_cmp_lt_f32_e64 vcc, |v93|, s34
	v_cndmask_b32_e32 v93, v93, v101, vcc
	v_cmp_lt_f32_e64 vcc, |v94|, s34
	v_cndmask_b32_e32 v94, v94, v102, vcc
	v_cmp_lt_f32_e64 vcc, |v95|, s34
	v_cndmask_b32_e32 v95, v95, v103, vcc
	v_cndmask_b32_e64 v100, 0, v213, s[22:23]
	v_cndmask_b32_e64 v101, 0, v213, s[24:25]
	v_cndmask_b32_e64 v102, 0, v213, s[26:27]
	v_cndmask_b32_e64 v103, 0, v213, s[28:29]
	v_sub_f32_e32 v92, v92, v100
	v_sub_f32_e32 v93, v93, v101
	v_sub_f32_e32 v94, v94, v102
	v_sub_f32_e32 v95, v95, v103
	v_add_f32_e32 v64, v64, v92
	v_add_f32_e32 v65, v65, v93
	v_add_f32_e32 v66, v66, v94
	v_add_f32_e32 v67, v67, v95
	v_mul_f32_e32 v92, 0xbfb8aa3b, v64
	v_mul_f32_e32 v93, 0xbfb8aa3b, v65
	v_mul_f32_e32 v94, 0xbfb8aa3b, v66
	v_mul_f32_e32 v95, 0xbfb8aa3b, v67
	v_mul_f32_e32 v100, 0x3fb8aa3b, v64
	v_mul_f32_e32 v101, 0x3fb8aa3b, v65
	v_mul_f32_e32 v102, 0x3fb8aa3b, v66
	v_mul_f32_e32 v103, 0x3fb8aa3b, v67
	v_exp_f32_e32 v92, v92
	v_exp_f32_e32 v93, v93
	v_exp_f32_e32 v94, v94
	v_exp_f32_e32 v95, v95
	v_exp_f32_e32 v100, v100
	v_exp_f32_e32 v101, v101
	v_exp_f32_e32 v102, v102
	v_exp_f32_e32 v103, v103
	v_sub_f32_e32 v96, 1.0, v96
	v_sub_f32_e32 v97, 1.0, v97
	v_sub_f32_e32 v98, 1.0, v98
	v_sub_f32_e32 v99, 1.0, v99
	v_mul_f32_e32 v96, v96, v92
	v_mul_f32_e32 v97, v97, v93
	v_mul_f32_e32 v98, v98, v94
	v_mul_f32_e32 v99, v99, v95
	v_lshlrev_b32_e32 v92, 16, v46
	v_and_b32_e32 v93, 0xffff0000, v46
	v_lshlrev_b32_e32 v94, 16, v47
	v_and_b32_e32 v95, 0xffff0000, v47
	v_mul_f32_e32 v92, v92, v100
	v_mul_f32_e32 v93, v93, v101
	v_mul_f32_e32 v94, v94, v102
	v_mul_f32_e32 v95, v95, v103
	v_cvt_pk_bf16_f32 v129, v129, v96
	v_cvt_pk_bf16_f32 v145, v145, v97
	v_cvt_pk_bf16_f32 v179, v179, v98
	v_cvt_pk_bf16_f32 v195, v195, v99
	v_cvt_pk_bf16_f32 v92, v92, v93
	v_cvt_pk_bf16_f32 v93, v94, v95
	v_cvt_pk_bf16_f32 v96, v96, v97
	v_cvt_pk_bf16_f32 v97, v98, v99
	global_store_dwordx2 v112, v[92:93], s[2:3]
	global_store_dwordx2 v114, v[96:97], s[2:3]
	s_add_u32 s2, s2, 0x400
	s_addc_u32 s3, s3, 0
	v_lshlrev_b32_e32 v92, 16, v48
	v_and_b32_e32 v93, 0xffff0000, v48
	v_lshlrev_b32_e32 v94, 16, v49
	v_and_b32_e32 v95, 0xffff0000, v49
	v_mul_f32_e32 v92, 0xbfb8aa3b, v92
	v_mul_f32_e32 v93, 0xbfb8aa3b, v93
	v_mul_f32_e32 v94, 0xbfb8aa3b, v94
	v_mul_f32_e32 v95, 0xbfb8aa3b, v95
	v_exp_f32_e32 v92, v92
	v_exp_f32_e32 v93, v93
	v_exp_f32_e32 v94, v94
	v_exp_f32_e32 v95, v95
	v_add_f32_e32 v92, 1.0, v92
	v_add_f32_e32 v93, 1.0, v93
	v_add_f32_e32 v94, 1.0, v94
	v_add_f32_e32 v95, 1.0, v95
	v_rcp_f32_e32 v92, v92
	v_rcp_f32_e32 v93, v93
	v_rcp_f32_e32 v94, v94
	v_rcp_f32_e32 v95, v95
	v_fma_f32 v96, v72, v92, v68
	v_fma_f32 v97, v73, v93, v69
	v_fma_f32 v98, v74, v94, v70
	v_fma_f32 v99, v75, v95, v71
	v_cmp_gt_f32_e64 s[22:23], s30, v96
	v_cmp_gt_f32_e64 s[24:25], s30, v97
	v_cmp_gt_f32_e64 s[26:27], s30, v98
	v_cmp_gt_f32_e64 s[28:29], s30, v99
	v_cndmask_b32_e64 v92, 0, 32, s[22:23]
	v_cndmask_b32_e64 v93, 0, 32, s[24:25]
	v_cndmask_b32_e64 v94, 0, 32, s[26:27]
	v_cndmask_b32_e64 v95, 0, 32, s[28:29]
	v_ldexp_f32 v92, v96, v92
	v_ldexp_f32 v93, v97, v93
	v_ldexp_f32 v94, v98, v94
	v_ldexp_f32 v95, v99, v95
	v_log_f32_e32 v92, v92
	v_log_f32_e32 v93, v93
	v_log_f32_e32 v94, v94
	v_log_f32_e32 v95, v95
	v_mul_f32_e32 v100, 0x3f317217, v92
	v_mul_f32_e32 v101, 0x3f317217, v93
	v_mul_f32_e32 v102, 0x3f317217, v94
	v_mul_f32_e32 v103, 0x3f317217, v95
	v_fma_f32 v100, v92, s31, -v100
; DEV u16 f2bf(float f) { return (u16)(pack2(f, f) & 0xffffu); }
; DEV float bf2f(u16 h) { return __uint_as_float(((unsigned)h) << 16); }
; DEV float sigmoid_f(float x) { return __builtin_amdgcn_rcpf(1.f + __expf(-x)); }
; DEV void phase_p15(const Params& p, int g) {
;     ...
; #pragma unroll
;       for (int cc = 0; cc < 2; ++cc) {
;         const int c = tid + 256 * cc;
;         unsigned kb[8];
; #pragma unroll
;         for (int e = 0; e < 8; ++e) {
;           const int jj = j8 * 8 + e;
;           const int j = dir ? 63 - jj : jj;
;           const size_t tok = (size_t)cidx * 64 + j;
;           const float f = lb[cc] + (1.f - lb[cc]) * sigmoid_f(bf2f(xr[st][cc][e]));
;           G[cc] += __logf(f);
;           const float eg = __expf(G[cc]), ig = __expf(-G[cc]);
;           Qp[tok * 512 + c] = f2bf(bf2f(qr[st][cc][e]) * eg);
;           const u16 kk = f2bf((1.f - f) * ig);
;           Kp[tok * 512 + c] = kk;
;           kb[e] = kk;
;         }
;         const int s0 = dir ? 56 - 8 * j8 : 8 * j8;
;         uint4 w;
;         w.x = dir ? (kb[7] | (kb[6] << 16)) : (kb[0] | (kb[1] << 16));
;         w.y = dir ? (kb[5] | (kb[4] << 16)) : (kb[2] | (kb[3] << 16));
;         w.z = dir ? (kb[3] | (kb[2] << 16)) : (kb[4] | (kb[5] << 16));
;         w.w = dir ? (kb[1] | (kb[0] << 16)) : (kb[6] | (kb[7] << 16));
;         *(uint4*)(KT + (((size_t)cidx * 2 + dir) * 512 + c) * 64 + s0) = w;
;       }
	v_fma_f32 v101, v93, s31, -v101
	v_fma_f32 v102, v94, s31, -v102
	v_fma_f32 v103, v95, s31, -v103
	v_fmac_f32_e32 v100, 0x3377d1cf, v92
	v_fmac_f32_e32 v101, 0x3377d1cf, v93
	v_fmac_f32_e32 v102, 0x3377d1cf, v94
	v_fmac_f32_e32 v103, 0x3377d1cf, v95
	v_fmac_f32_e32 v100, 0x3f317217, v92
	v_fmac_f32_e32 v101, 0x3f317217, v93
	v_fmac_f32_e32 v102, 0x3f317217, v94
	v_fmac_f32_e32 v103, 0x3f317217, v95
	v_cmp_lt_f32_e64 vcc, |v92|, s34
	v_cndmask_b32_e32 v92, v92, v100, vcc
	v_cmp_lt_f32_e64 vcc, |v93|, s34
	v_cndmask_b32_e32 v93, v93, v101, vcc
	v_cmp_lt_f32_e64 vcc, |v94|, s34
	v_cndmask_b32_e32 v94, v94, v102, vcc
	v_cmp_lt_f32_e64 vcc, |v95|, s34
	v_cndmask_b32_e32 v95, v95, v103, vcc
	v_cndmask_b32_e64 v100, 0, v213, s[22:23]
	v_cndmask_b32_e64 v101, 0, v213, s[24:25]
	v_cndmask_b32_e64 v102, 0, v213, s[26:27]
	v_cndmask_b32_e64 v103, 0, v213, s[28:29]
	v_sub_f32_e32 v92, v92, v100
	v_sub_f32_e32 v93, v93, v101
	v_sub_f32_e32 v94, v94, v102
	v_sub_f32_e32 v95, v95, v103
	v_add_f32_e32 v64, v64, v92
	v_add_f32_e32 v65, v65, v93
	v_add_f32_e32 v66, v66, v94
	v_add_f32_e32 v67, v67, v95
	v_mul_f32_e32 v92, 0xbfb8aa3b, v64
	v_mul_f32_e32 v93, 0xbfb8aa3b, v65
	v_mul_f32_e32 v94, 0xbfb8aa3b, v66
	v_mul_f32_e32 v95, 0xbfb8aa3b, v67
	v_mul_f32_e32 v100, 0x3fb8aa3b, v64
	v_mul_f32_e32 v101, 0x3fb8aa3b, v65
	v_mul_f32_e32 v102, 0x3fb8aa3b, v66
	v_mul_f32_e32 v103, 0x3fb8aa3b, v67
	v_exp_f32_e32 v92, v92
	v_exp_f32_e32 v93, v93
	v_exp_f32_e32 v94, v94
	v_exp_f32_e32 v95, v95
	v_exp_f32_e32 v100, v100
	v_exp_f32_e32 v101, v101
	v_exp_f32_e32 v102, v102
	v_exp_f32_e32 v103, v103
	v_sub_f32_e32 v96, 1.0, v96
	v_sub_f32_e32 v97, 1.0, v97
	v_sub_f32_e32 v98, 1.0, v98
	v_sub_f32_e32 v99, 1.0, v99
	v_mul_f32_e32 v96, v96, v92
	v_mul_f32_e32 v97, v97, v93
	v_mul_f32_e32 v98, v98, v94
	v_mul_f32_e32 v99, v99, v95
	v_lshlrev_b32_e32 v92, 16, v50
	v_and_b32_e32 v93, 0xffff0000, v50
	v_lshlrev_b32_e32 v94, 16, v51
	v_and_b32_e32 v95, 0xffff0000, v51
	v_mul_f32_e32 v92, v92, v100
	v_mul_f32_e32 v93, v93, v101
	v_mul_f32_e32 v94, v94, v102
	v_mul_f32_e32 v95, v95, v103
	v_mov_b32_e32 v130, v96
	v_mov_b32_e32 v146, v97
	v_mov_b32_e32 v180, v98
	v_mov_b32_e32 v196, v99
	v_cvt_pk_bf16_f32 v92, v92, v93
	v_cvt_pk_bf16_f32 v93, v94, v95
	v_cvt_pk_bf16_f32 v96, v96, v97
	v_cvt_pk_bf16_f32 v97, v98, v99
	global_store_dwordx2 v112, v[92:93], s[2:3]
	global_store_dwordx2 v114, v[96:97], s[2:3]
	s_add_u32 s2, s2, 0x400
	s_addc_u32 s3, s3, 0
	v_lshlrev_b32_e32 v92, 16, v52
	v_and_b32_e32 v93, 0xffff0000, v52
	v_lshlrev_b32_e32 v94, 16, v53
	v_and_b32_e32 v95, 0xffff0000, v53
	v_mul_f32_e32 v92, 0xbfb8aa3b, v92
	v_mul_f32_e32 v93, 0xbfb8aa3b, v93
	v_mul_f32_e32 v94, 0xbfb8aa3b, v94
	v_mul_f32_e32 v95, 0xbfb8aa3b, v95
	v_exp_f32_e32 v92, v92
	v_exp_f32_e32 v93, v93
	v_exp_f32_e32 v94, v94
	v_exp_f32_e32 v95, v95
	v_add_f32_e32 v92, 1.0, v92
	v_add_f32_e32 v93, 1.0, v93
	v_add_f32_e32 v94, 1.0, v94
	v_add_f32_e32 v95, 1.0, v95
	v_rcp_f32_e32 v92, v92
	v_rcp_f32_e32 v93, v93
	v_rcp_f32_e32 v94, v94
	v_rcp_f32_e32 v95, v95
	v_fma_f32 v96, v72, v92, v68
	v_fma_f32 v97, v73, v93, v69
	v_fma_f32 v98, v74, v94, v70
	v_fma_f32 v99, v75, v95, v71
	v_cmp_gt_f32_e64 s[22:23], s30, v96
	v_cmp_gt_f32_e64 s[24:25], s30, v97
	v_cmp_gt_f32_e64 s[26:27], s30, v98
	v_cmp_gt_f32_e64 s[28:29], s30, v99
	v_cndmask_b32_e64 v92, 0, 32, s[22:23]
	v_cndmask_b32_e64 v93, 0, 32, s[24:25]
	v_cndmask_b32_e64 v94, 0, 32, s[26:27]
	v_cndmask_b32_e64 v95, 0, 32, s[28:29]
	v_ldexp_f32 v92, v96, v92
	v_ldexp_f32 v93, v97, v93
	v_ldexp_f32 v94, v98, v94
	v_ldexp_f32 v95, v99, v95
	v_log_f32_e32 v92, v92
	v_log_f32_e32 v93, v93
	v_log_f32_e32 v94, v94
	v_log_f32_e32 v95, v95
	v_mul_f32_e32 v100, 0x3f317217, v92
	v_mul_f32_e32 v101, 0x3f317217, v93
	v_mul_f32_e32 v102, 0x3f317217, v94
	v_mul_f32_e32 v103, 0x3f317217, v95
	v_fma_f32 v100, v92, s31, -v100
	v_fma_f32 v101, v93, s31, -v101
	v_fma_f32 v102, v94, s31, -v102
	v_fma_f32 v103, v95, s31, -v103
	v_fmac_f32_e32 v100, 0x3377d1cf, v92
	v_fmac_f32_e32 v101, 0x3377d1cf, v93
	v_fmac_f32_e32 v102, 0x3377d1cf, v94
	v_fmac_f32_e32 v103, 0x3377d1cf, v95
	v_fmac_f32_e32 v100, 0x3f317217, v92
	v_fmac_f32_e32 v101, 0x3f317217, v93
	v_fmac_f32_e32 v102, 0x3f317217, v94
	v_fmac_f32_e32 v103, 0x3f317217, v95
	v_cmp_lt_f32_e64 vcc, |v92|, s34
	v_cndmask_b32_e32 v92, v92, v100, vcc
	v_cmp_lt_f32_e64 vcc, |v93|, s34
	v_cndmask_b32_e32 v93, v93, v101, vcc
	v_cmp_lt_f32_e64 vcc, |v94|, s34
	v_cndmask_b32_e32 v94, v94, v102, vcc
	v_cmp_lt_f32_e64 vcc, |v95|, s34
	v_cndmask_b32_e32 v95, v95, v103, vcc
	v_cndmask_b32_e64 v100, 0, v213, s[22:23]
	v_cndmask_b32_e64 v101, 0, v213, s[24:25]
	v_cndmask_b32_e64 v102, 0, v213, s[26:27]
	v_cndmask_b32_e64 v103, 0, v213, s[28:29]
	v_sub_f32_e32 v92, v92, v100
	v_sub_f32_e32 v93, v93, v101
	v_sub_f32_e32 v94, v94, v102
	v_sub_f32_e32 v95, v95, v103
	v_add_f32_e32 v64, v64, v92
	v_add_f32_e32 v65, v65, v93
	v_add_f32_e32 v66, v66, v94
	v_add_f32_e32 v67, v67, v95
	v_mul_f32_e32 v92, 0xbfb8aa3b, v64
	v_mul_f32_e32 v93, 0xbfb8aa3b, v65
	v_mul_f32_e32 v94, 0xbfb8aa3b, v66
	v_mul_f32_e32 v95, 0xbfb8aa3b, v67
	v_mul_f32_e32 v100, 0x3fb8aa3b, v64
	v_mul_f32_e32 v101, 0x3fb8aa3b, v65
	v_mul_f32_e32 v102, 0x3fb8aa3b, v66
	v_mul_f32_e32 v103, 0x3fb8aa3b, v67
	v_exp_f32_e32 v92, v92
	v_exp_f32_e32 v93, v93
	v_exp_f32_e32 v94, v94
	v_exp_f32_e32 v95, v95
	v_exp_f32_e32 v100, v100
	v_exp_f32_e32 v101, v101
	v_exp_f32_e32 v102, v102
	v_exp_f32_e32 v103, v103
	v_sub_f32_e32 v96, 1.0, v96
	v_sub_f32_e32 v97, 1.0, v97
	v_sub_f32_e32 v98, 1.0, v98
	v_sub_f32_e32 v99, 1.0, v99
	v_mul_f32_e32 v96, v96, v92
	v_mul_f32_e32 v97, v97, v93
	v_mul_f32_e32 v98, v98, v94
; DEV u16 f2bf(float f) { return (u16)(pack2(f, f) & 0xffffu); }
; DEV float bf2f(u16 h) { return __uint_as_float(((unsigned)h) << 16); }
; DEV float sigmoid_f(float x) { return __builtin_amdgcn_rcpf(1.f + __expf(-x)); }
; DEV void phase_p15(const Params& p, int g) {
;     ...
; #pragma unroll
;       for (int cc = 0; cc < 2; ++cc) {
;         const int c = tid + 256 * cc;
;         unsigned kb[8];
; #pragma unroll
;         for (int e = 0; e < 8; ++e) {
;           const int jj = j8 * 8 + e;
;           const int j = dir ? 63 - jj : jj;
;           const size_t tok = (size_t)cidx * 64 + j;
;           const float f = lb[cc] + (1.f - lb[cc]) * sigmoid_f(bf2f(xr[st][cc][e]));
;           G[cc] += __logf(f);
;           const float eg = __expf(G[cc]), ig = __expf(-G[cc]);
;           Qp[tok * 512 + c] = f2bf(bf2f(qr[st][cc][e]) * eg);
;           const u16 kk = f2bf((1.f - f) * ig);
;           Kp[tok * 512 + c] = kk;
;           kb[e] = kk;
;         }
;         const int s0 = dir ? 56 - 8 * j8 : 8 * j8;
;         uint4 w;
;         w.x = dir ? (kb[7] | (kb[6] << 16)) : (kb[0] | (kb[1] << 16));
;         w.y = dir ? (kb[5] | (kb[4] << 16)) : (kb[2] | (kb[3] << 16));
;         w.z = dir ? (kb[3] | (kb[2] << 16)) : (kb[4] | (kb[5] << 16));
;         w.w = dir ? (kb[1] | (kb[0] << 16)) : (kb[6] | (kb[7] << 16));
;         *(uint4*)(KT + (((size_t)cidx * 2 + dir) * 512 + c) * 64 + s0) = w;
;       }
	v_mul_f32_e32 v99, v99, v95
	v_lshlrev_b32_e32 v92, 16, v54
	v_and_b32_e32 v93, 0xffff0000, v54
	v_lshlrev_b32_e32 v94, 16, v55
	v_and_b32_e32 v95, 0xffff0000, v55
	v_mul_f32_e32 v92, v92, v100
	v_mul_f32_e32 v93, v93, v101
	v_mul_f32_e32 v94, v94, v102
	v_mul_f32_e32 v95, v95, v103
	v_cvt_pk_bf16_f32 v130, v130, v96
	v_cvt_pk_bf16_f32 v146, v146, v97
	v_cvt_pk_bf16_f32 v180, v180, v98
	v_cvt_pk_bf16_f32 v196, v196, v99
	v_cvt_pk_bf16_f32 v92, v92, v93
	v_cvt_pk_bf16_f32 v93, v94, v95
	v_cvt_pk_bf16_f32 v96, v96, v97
	v_cvt_pk_bf16_f32 v97, v98, v99
	global_store_dwordx2 v112, v[92:93], s[2:3]
	global_store_dwordx2 v114, v[96:97], s[2:3]
	s_add_u32 s2, s2, 0x400
	s_addc_u32 s3, s3, 0
	v_lshlrev_b32_e32 v92, 16, v56
	v_and_b32_e32 v93, 0xffff0000, v56
	v_lshlrev_b32_e32 v94, 16, v57
	v_and_b32_e32 v95, 0xffff0000, v57
	v_mul_f32_e32 v92, 0xbfb8aa3b, v92
	v_mul_f32_e32 v93, 0xbfb8aa3b, v93
	v_mul_f32_e32 v94, 0xbfb8aa3b, v94
	v_mul_f32_e32 v95, 0xbfb8aa3b, v95
	v_exp_f32_e32 v92, v92
	v_exp_f32_e32 v93, v93
	v_exp_f32_e32 v94, v94
	v_exp_f32_e32 v95, v95
	v_add_f32_e32 v92, 1.0, v92
	v_add_f32_e32 v93, 1.0, v93
	v_add_f32_e32 v94, 1.0, v94
	v_add_f32_e32 v95, 1.0, v95
	v_rcp_f32_e32 v92, v92
	v_rcp_f32_e32 v93, v93
	v_rcp_f32_e32 v94, v94
	v_rcp_f32_e32 v95, v95
	v_fma_f32 v96, v72, v92, v68
	v_fma_f32 v97, v73, v93, v69
	v_fma_f32 v98, v74, v94, v70
	v_fma_f32 v99, v75, v95, v71
	v_cmp_gt_f32_e64 s[22:23], s30, v96
	v_cmp_gt_f32_e64 s[24:25], s30, v97
	v_cmp_gt_f32_e64 s[26:27], s30, v98
	v_cmp_gt_f32_e64 s[28:29], s30, v99
	v_cndmask_b32_e64 v92, 0, 32, s[22:23]
	v_cndmask_b32_e64 v93, 0, 32, s[24:25]
	v_cndmask_b32_e64 v94, 0, 32, s[26:27]
	v_cndmask_b32_e64 v95, 0, 32, s[28:29]
	v_ldexp_f32 v92, v96, v92
	v_ldexp_f32 v93, v97, v93
	v_ldexp_f32 v94, v98, v94
	v_ldexp_f32 v95, v99, v95
	v_log_f32_e32 v92, v92
	v_log_f32_e32 v93, v93
	v_log_f32_e32 v94, v94
	v_log_f32_e32 v95, v95
	v_mul_f32_e32 v100, 0x3f317217, v92
	v_mul_f32_e32 v101, 0x3f317217, v93
	v_mul_f32_e32 v102, 0x3f317217, v94
	v_mul_f32_e32 v103, 0x3f317217, v95
	v_fma_f32 v100, v92, s31, -v100
	v_fma_f32 v101, v93, s31, -v101
	v_fma_f32 v102, v94, s31, -v102
	v_fma_f32 v103, v95, s31, -v103
	v_fmac_f32_e32 v100, 0x3377d1cf, v92
	v_fmac_f32_e32 v101, 0x3377d1cf, v93
	v_fmac_f32_e32 v102, 0x3377d1cf, v94
	v_fmac_f32_e32 v103, 0x3377d1cf, v95
	v_fmac_f32_e32 v100, 0x3f317217, v92
	v_fmac_f32_e32 v101, 0x3f317217, v93
	v_fmac_f32_e32 v102, 0x3f317217, v94
	v_fmac_f32_e32 v103, 0x3f317217, v95
	v_cmp_lt_f32_e64 vcc, |v92|, s34
	v_cndmask_b32_e32 v92, v92, v100, vcc
	v_cmp_lt_f32_e64 vcc, |v93|, s34
	v_cndmask_b32_e32 v93, v93, v101, vcc
	v_cmp_lt_f32_e64 vcc, |v94|, s34
	v_cndmask_b32_e32 v94, v94, v102, vcc
	v_cmp_lt_f32_e64 vcc, |v95|, s34
	v_cndmask_b32_e32 v95, v95, v103, vcc
	v_cndmask_b32_e64 v100, 0, v213, s[22:23]
	v_cndmask_b32_e64 v101, 0, v213, s[24:25]
	v_cndmask_b32_e64 v102, 0, v213, s[26:27]
	v_cndmask_b32_e64 v103, 0, v213, s[28:29]
	v_sub_f32_e32 v92, v92, v100
	v_sub_f32_e32 v93, v93, v101
	v_sub_f32_e32 v94, v94, v102
	v_sub_f32_e32 v95, v95, v103
	v_add_f32_e32 v64, v64, v92
	v_add_f32_e32 v65, v65, v93
	v_add_f32_e32 v66, v66, v94
	v_add_f32_e32 v67, v67, v95
	v_mul_f32_e32 v92, 0xbfb8aa3b, v64
	v_mul_f32_e32 v93, 0xbfb8aa3b, v65
	v_mul_f32_e32 v94, 0xbfb8aa3b, v66
	v_mul_f32_e32 v95, 0xbfb8aa3b, v67
	v_mul_f32_e32 v100, 0x3fb8aa3b, v64
	v_mul_f32_e32 v101, 0x3fb8aa3b, v65
	v_mul_f32_e32 v102, 0x3fb8aa3b, v66
	v_mul_f32_e32 v103, 0x3fb8aa3b, v67
	v_exp_f32_e32 v92, v92
	v_exp_f32_e32 v93, v93
	v_exp_f32_e32 v94, v94
	v_exp_f32_e32 v95, v95
	v_exp_f32_e32 v100, v100
	v_exp_f32_e32 v101, v101
	v_exp_f32_e32 v102, v102
	v_exp_f32_e32 v103, v103
	v_sub_f32_e32 v96, 1.0, v96
	v_sub_f32_e32 v97, 1.0, v97
	v_sub_f32_e32 v98, 1.0, v98
	v_sub_f32_e32 v99, 1.0, v99
	v_mul_f32_e32 v96, v96, v92
	v_mul_f32_e32 v97, v97, v93
	v_mul_f32_e32 v98, v98, v94
	v_mul_f32_e32 v99, v99, v95
	v_lshlrev_b32_e32 v92, 16, v58
	v_and_b32_e32 v93, 0xffff0000, v58
	v_lshlrev_b32_e32 v94, 16, v59
	v_and_b32_e32 v95, 0xffff0000, v59
	v_mul_f32_e32 v92, v92, v100
	v_mul_f32_e32 v93, v93, v101
	v_mul_f32_e32 v94, v94, v102
	v_mul_f32_e32 v95, v95, v103
	v_mov_b32_e32 v131, v96
	v_mov_b32_e32 v147, v97
	v_mov_b32_e32 v181, v98
	v_mov_b32_e32 v197, v99
	v_cvt_pk_bf16_f32 v92, v92, v93
	v_cvt_pk_bf16_f32 v93, v94, v95
	v_cvt_pk_bf16_f32 v96, v96, v97
	v_cvt_pk_bf16_f32 v97, v98, v99
	global_store_dwordx2 v112, v[92:93], s[2:3]
	global_store_dwordx2 v114, v[96:97], s[2:3]
	s_add_u32 s2, s2, 0x400
	s_addc_u32 s3, s3, 0
	v_lshlrev_b32_e32 v92, 16, v60
	v_and_b32_e32 v93, 0xffff0000, v60
	v_lshlrev_b32_e32 v94, 16, v61
	v_and_b32_e32 v95, 0xffff0000, v61
	v_mul_f32_e32 v92, 0xbfb8aa3b, v92
	v_mul_f32_e32 v93, 0xbfb8aa3b, v93
	v_mul_f32_e32 v94, 0xbfb8aa3b, v94
; DEV u16 f2bf(float f) { return (u16)(pack2(f, f) & 0xffffu); }
; DEV float bf2f(u16 h) { return __uint_as_float(((unsigned)h) << 16); }
; DEV float sigmoid_f(float x) { return __builtin_amdgcn_rcpf(1.f + __expf(-x)); }
; DEV void phase_p15(const Params& p, int g) {
;     ...
;     P15_LOAD(0, 0);
;     P15_LOAD(1, 1);
; #pragma unroll
;     for (int j8 = 0; j8 < 8; ++j8) {
;       const int st = j8 % 3;
;       if (j8 < 6) { P15_LOAD((j8 + 2) % 3, j8 + 2); }
; #pragma unroll
;       for (int cc = 0; cc < 2; ++cc) {
;         const int c = tid + 256 * cc;
;         unsigned kb[8];
; #pragma unroll
;         for (int e = 0; e < 8; ++e) {
;           const int jj = j8 * 8 + e;
;           const int j = dir ? 63 - jj : jj;
;           const size_t tok = (size_t)cidx * 64 + j;
;           const float f = lb[cc] + (1.f - lb[cc]) * sigmoid_f(bf2f(xr[st][cc][e]));
;           G[cc] += __logf(f);
;           const float eg = __expf(G[cc]), ig = __expf(-G[cc]);
;           Qp[tok * 512 + c] = f2bf(bf2f(qr[st][cc][e]) * eg);
;           const u16 kk = f2bf((1.f - f) * ig);
;           Kp[tok * 512 + c] = kk;
;           kb[e] = kk;
;         }
;         const int s0 = dir ? 56 - 8 * j8 : 8 * j8;
;         uint4 w;
;         w.x = dir ? (kb[7] | (kb[6] << 16)) : (kb[0] | (kb[1] << 16));
;         w.y = dir ? (kb[5] | (kb[4] << 16)) : (kb[2] | (kb[3] << 16));
;         w.z = dir ? (kb[3] | (kb[2] << 16)) : (kb[4] | (kb[5] << 16));
;         w.w = dir ? (kb[1] | (kb[0] << 16)) : (kb[6] | (kb[7] << 16));
;         *(uint4*)(KT + (((size_t)cidx * 2 + dir) * 512 + c) * 64 + s0) = w;
;       }
	v_mul_f32_e32 v95, 0xbfb8aa3b, v95
	v_exp_f32_e32 v92, v92
	v_exp_f32_e32 v93, v93
	v_exp_f32_e32 v94, v94
	v_exp_f32_e32 v95, v95
	v_add_f32_e32 v92, 1.0, v92
	v_add_f32_e32 v93, 1.0, v93
	v_add_f32_e32 v94, 1.0, v94
	v_add_f32_e32 v95, 1.0, v95
	v_rcp_f32_e32 v92, v92
	v_rcp_f32_e32 v93, v93
	v_rcp_f32_e32 v94, v94
	v_rcp_f32_e32 v95, v95
	v_fma_f32 v96, v72, v92, v68
	v_fma_f32 v97, v73, v93, v69
	v_fma_f32 v98, v74, v94, v70
	v_fma_f32 v99, v75, v95, v71
	v_cmp_gt_f32_e64 s[22:23], s30, v96
	v_cmp_gt_f32_e64 s[24:25], s30, v97
	v_cmp_gt_f32_e64 s[26:27], s30, v98
	v_cmp_gt_f32_e64 s[28:29], s30, v99
	v_cndmask_b32_e64 v92, 0, 32, s[22:23]
	v_cndmask_b32_e64 v93, 0, 32, s[24:25]
	v_cndmask_b32_e64 v94, 0, 32, s[26:27]
	v_cndmask_b32_e64 v95, 0, 32, s[28:29]
	v_ldexp_f32 v92, v96, v92
	v_ldexp_f32 v93, v97, v93
	v_ldexp_f32 v94, v98, v94
	v_ldexp_f32 v95, v99, v95
	v_log_f32_e32 v92, v92
	v_log_f32_e32 v93, v93
	v_log_f32_e32 v94, v94
	v_log_f32_e32 v95, v95
	v_mul_f32_e32 v100, 0x3f317217, v92
	v_mul_f32_e32 v101, 0x3f317217, v93
	v_mul_f32_e32 v102, 0x3f317217, v94
	v_mul_f32_e32 v103, 0x3f317217, v95
	v_fma_f32 v100, v92, s31, -v100
	v_fma_f32 v101, v93, s31, -v101
	v_fma_f32 v102, v94, s31, -v102
	v_fma_f32 v103, v95, s31, -v103
	v_fmac_f32_e32 v100, 0x3377d1cf, v92
	v_fmac_f32_e32 v101, 0x3377d1cf, v93
	v_fmac_f32_e32 v102, 0x3377d1cf, v94
	v_fmac_f32_e32 v103, 0x3377d1cf, v95
	v_fmac_f32_e32 v100, 0x3f317217, v92
	v_fmac_f32_e32 v101, 0x3f317217, v93
	v_fmac_f32_e32 v102, 0x3f317217, v94
	v_fmac_f32_e32 v103, 0x3f317217, v95
	v_cmp_lt_f32_e64 vcc, |v92|, s34
	v_cndmask_b32_e32 v92, v92, v100, vcc
	v_cmp_lt_f32_e64 vcc, |v93|, s34
	v_cndmask_b32_e32 v93, v93, v101, vcc
	v_cmp_lt_f32_e64 vcc, |v94|, s34
	v_cndmask_b32_e32 v94, v94, v102, vcc
	v_cmp_lt_f32_e64 vcc, |v95|, s34
	v_cndmask_b32_e32 v95, v95, v103, vcc
	v_cndmask_b32_e64 v100, 0, v213, s[22:23]
	v_cndmask_b32_e64 v101, 0, v213, s[24:25]
	v_cndmask_b32_e64 v102, 0, v213, s[26:27]
	v_cndmask_b32_e64 v103, 0, v213, s[28:29]
	v_sub_f32_e32 v92, v92, v100
	v_sub_f32_e32 v93, v93, v101
	v_sub_f32_e32 v94, v94, v102
	v_sub_f32_e32 v95, v95, v103
	v_add_f32_e32 v64, v64, v92
	v_add_f32_e32 v65, v65, v93
	v_add_f32_e32 v66, v66, v94
	v_add_f32_e32 v67, v67, v95
	v_mul_f32_e32 v92, 0xbfb8aa3b, v64
	v_mul_f32_e32 v93, 0xbfb8aa3b, v65
	v_mul_f32_e32 v94, 0xbfb8aa3b, v66
	v_mul_f32_e32 v95, 0xbfb8aa3b, v67
	v_mul_f32_e32 v100, 0x3fb8aa3b, v64
	v_mul_f32_e32 v101, 0x3fb8aa3b, v65
	v_mul_f32_e32 v102, 0x3fb8aa3b, v66
	v_mul_f32_e32 v103, 0x3fb8aa3b, v67
	v_exp_f32_e32 v92, v92
	v_exp_f32_e32 v93, v93
	v_exp_f32_e32 v94, v94
	v_exp_f32_e32 v95, v95
	v_exp_f32_e32 v100, v100
	v_exp_f32_e32 v101, v101
	v_exp_f32_e32 v102, v102
	v_exp_f32_e32 v103, v103
	v_sub_f32_e32 v96, 1.0, v96
	v_sub_f32_e32 v97, 1.0, v97
	v_sub_f32_e32 v98, 1.0, v98
	v_sub_f32_e32 v99, 1.0, v99
	v_mul_f32_e32 v96, v96, v92
	v_mul_f32_e32 v97, v97, v93
	v_mul_f32_e32 v98, v98, v94
	v_mul_f32_e32 v99, v99, v95
	v_lshlrev_b32_e32 v92, 16, v62
	v_and_b32_e32 v93, 0xffff0000, v62
	v_lshlrev_b32_e32 v94, 16, v63
	v_and_b32_e32 v95, 0xffff0000, v63
	v_mul_f32_e32 v92, v92, v100
	v_mul_f32_e32 v93, v93, v101
	v_mul_f32_e32 v94, v94, v102
	v_mul_f32_e32 v95, v95, v103
	v_cvt_pk_bf16_f32 v131, v131, v96
	v_cvt_pk_bf16_f32 v147, v147, v97
	v_cvt_pk_bf16_f32 v181, v181, v98
	v_cvt_pk_bf16_f32 v197, v197, v99
	v_cvt_pk_bf16_f32 v92, v92, v93
	v_cvt_pk_bf16_f32 v93, v94, v95
	v_cvt_pk_bf16_f32 v96, v96, v97
	v_cvt_pk_bf16_f32 v97, v98, v99
	global_store_dwordx2 v112, v[92:93], s[2:3]
	global_store_dwordx2 v114, v[96:97], s[2:3]
	s_add_u32 s2, s2, 0x400
	s_addc_u32 s3, s3, 0
	s_cmp_eq_u32 s35, 1
	s_cbranch_scc1 .Lp15_d0_nl3
	global_load_dwordx2 v[32:33], v113, s[0:1]
	global_load_dwordx2 v[34:35], v112, s[0:1]
	s_add_u32 s0, s0, 0x1400
	s_addc_u32 s1, s1, 0
	global_load_dwordx2 v[36:37], v113, s[0:1]
	global_load_dwordx2 v[38:39], v112, s[0:1]
	s_add_u32 s0, s0, 0x1400
	s_addc_u32 s1, s1, 0
	global_load_dwordx2 v[40:41], v113, s[0:1]
	global_load_dwordx2 v[42:43], v112, s[0:1]
	s_add_u32 s0, s0, 0x1400
	s_addc_u32 s1, s1, 0
	global_load_dwordx2 v[44:45], v113, s[0:1]
	global_load_dwordx2 v[46:47], v112, s[0:1]
	s_add_u32 s0, s0, 0x1400
	s_addc_u32 s1, s1, 0
	global_load_dwordx2 v[48:49], v113, s[0:1]
	global_load_dwordx2 v[50:51], v112, s[0:1]
	s_add_u32 s0, s0, 0x1400
	s_addc_u32 s1, s1, 0
	global_load_dwordx2 v[52:53], v113, s[0:1]
	global_load_dwordx2 v[54:55], v112, s[0:1]
	s_add_u32 s0, s0, 0x1400
	s_addc_u32 s1, s1, 0
	global_load_dwordx2 v[56:57], v113, s[0:1]
	global_load_dwordx2 v[58:59], v112, s[0:1]
	s_add_u32 s0, s0, 0x1400
	s_addc_u32 s1, s1, 0
	global_load_dwordx2 v[60:61], v113, s[0:1]
	global_load_dwordx2 v[62:63], v112, s[0:1]
	s_add_u32 s0, s0, 0x1400
	s_addc_u32 s1, s1, 0

; DEV u16 f2bf(float f) { return (u16)(pack2(f, f) & 0xffffu); }
; DEV float bf2f(u16 h) { return __uint_as_float(((unsigned)h) << 16); }
; DEV float sigmoid_f(float x) { return __builtin_amdgcn_rcpf(1.f + __expf(-x)); }
; DEV void phase_p15(const Params& p, int g) {
;     ...
; #pragma unroll
;       for (int cc = 0; cc < 2; ++cc) {
;         const int c = tid + 256 * cc;
;         unsigned kb[8];
; #pragma unroll
;         for (int e = 0; e < 8; ++e) {
;           const int jj = j8 * 8 + e;
;           const int j = dir ? 63 - jj : jj;
;           const size_t tok = (size_t)cidx * 64 + j;
;           const float f = lb[cc] + (1.f - lb[cc]) * sigmoid_f(bf2f(xr[st][cc][e]));
;           G[cc] += __logf(f);
;           const float eg = __expf(G[cc]), ig = __expf(-G[cc]);
;           Qp[tok * 512 + c] = f2bf(bf2f(qr[st][cc][e]) * eg);
;           const u16 kk = f2bf((1.f - f) * ig);
;           Kp[tok * 512 + c] = kk;
;           kb[e] = kk;
;         }
;         const int s0 = dir ? 56 - 8 * j8 : 8 * j8;
;         uint4 w;
;         w.x = dir ? (kb[7] | (kb[6] << 16)) : (kb[0] | (kb[1] << 16));
;         w.y = dir ? (kb[5] | (kb[4] << 16)) : (kb[2] | (kb[3] << 16));
;         w.z = dir ? (kb[3] | (kb[2] << 16)) : (kb[4] | (kb[5] << 16));
;         w.w = dir ? (kb[1] | (kb[0] << 16)) : (kb[6] | (kb[7] << 16));
;         *(uint4*)(KT + (((size_t)cidx * 2 + dir) * 512 + c) * 64 + s0) = w;
;       }
.Lp15_wd_1:
	v_lshlrev_b32_e32 v92, 16, v32
	v_and_b32_e32 v93, 0xffff0000, v32
	v_lshlrev_b32_e32 v94, 16, v33
	v_and_b32_e32 v95, 0xffff0000, v33
	v_mul_f32_e32 v92, 0xbfb8aa3b, v92
	v_mul_f32_e32 v93, 0xbfb8aa3b, v93
	v_mul_f32_e32 v94, 0xbfb8aa3b, v94
	v_mul_f32_e32 v95, 0xbfb8aa3b, v95
	v_exp_f32_e32 v92, v92
	v_exp_f32_e32 v93, v93
	v_exp_f32_e32 v94, v94
	v_exp_f32_e32 v95, v95
	v_add_f32_e32 v92, 1.0, v92
	v_add_f32_e32 v93, 1.0, v93
	v_add_f32_e32 v94, 1.0, v94
	v_add_f32_e32 v95, 1.0, v95
	v_rcp_f32_e32 v92, v92
	v_rcp_f32_e32 v93, v93
	v_rcp_f32_e32 v94, v94
	v_rcp_f32_e32 v95, v95
	v_fma_f32 v96, v72, v92, v68
	v_fma_f32 v97, v73, v93, v69
	v_fma_f32 v98, v74, v94, v70
	v_fma_f32 v99, v75, v95, v71
	v_cmp_gt_f32_e64 s[22:23], s30, v96
	v_cmp_gt_f32_e64 s[24:25], s30, v97
	v_cmp_gt_f32_e64 s[26:27], s30, v98
	v_cmp_gt_f32_e64 s[28:29], s30, v99
	v_cndmask_b32_e64 v92, 0, 32, s[22:23]
	v_cndmask_b32_e64 v93, 0, 32, s[24:25]
	v_cndmask_b32_e64 v94, 0, 32, s[26:27]
	v_cndmask_b32_e64 v95, 0, 32, s[28:29]
	v_ldexp_f32 v92, v96, v92
	v_ldexp_f32 v93, v97, v93
	v_ldexp_f32 v94, v98, v94
	v_ldexp_f32 v95, v99, v95
	v_log_f32_e32 v92, v92
	v_log_f32_e32 v93, v93
	v_log_f32_e32 v94, v94
	v_log_f32_e32 v95, v95
	v_mul_f32_e32 v100, 0x3f317217, v92
	v_mul_f32_e32 v101, 0x3f317217, v93
	v_mul_f32_e32 v102, 0x3f317217, v94
	v_mul_f32_e32 v103, 0x3f317217, v95
	v_fma_f32 v100, v92, s31, -v100
	v_fma_f32 v101, v93, s31, -v101
	v_fma_f32 v102, v94, s31, -v102
	v_fma_f32 v103, v95, s31, -v103
	v_fmac_f32_e32 v100, 0x3377d1cf, v92
	v_fmac_f32_e32 v101, 0x3377d1cf, v93
	v_fmac_f32_e32 v102, 0x3377d1cf, v94
	v_fmac_f32_e32 v103, 0x3377d1cf, v95
	v_fmac_f32_e32 v100, 0x3f317217, v92
	v_fmac_f32_e32 v101, 0x3f317217, v93
	v_fmac_f32_e32 v102, 0x3f317217, v94
	v_fmac_f32_e32 v103, 0x3f317217, v95
	v_cmp_lt_f32_e64 vcc, |v92|, s34
	v_cndmask_b32_e32 v92, v92, v100, vcc
	v_cmp_lt_f32_e64 vcc, |v93|, s34
	v_cndmask_b32_e32 v93, v93, v101, vcc
	v_cmp_lt_f32_e64 vcc, |v94|, s34
	v_cndmask_b32_e32 v94, v94, v102, vcc
	v_cmp_lt_f32_e64 vcc, |v95|, s34
	v_cndmask_b32_e32 v95, v95, v103, vcc
	v_cndmask_b32_e64 v100, 0, v213, s[22:23]
	v_cndmask_b32_e64 v101, 0, v213, s[24:25]
	v_cndmask_b32_e64 v102, 0, v213, s[26:27]
	v_cndmask_b32_e64 v103, 0, v213, s[28:29]
	v_sub_f32_e32 v92, v92, v100
	v_sub_f32_e32 v93, v93, v101
	v_sub_f32_e32 v94, v94, v102
	v_sub_f32_e32 v95, v95, v103
	v_add_f32_e32 v64, v64, v92
	v_add_f32_e32 v65, v65, v93
	v_add_f32_e32 v66, v66, v94
	v_add_f32_e32 v67, v67, v95
	v_mul_f32_e32 v92, 0xbfb8aa3b, v64
	v_mul_f32_e32 v93, 0xbfb8aa3b, v65
	v_mul_f32_e32 v94, 0xbfb8aa3b, v66
	v_mul_f32_e32 v95, 0xbfb8aa3b, v67
	v_mul_f32_e32 v100, 0x3fb8aa3b, v64
	v_mul_f32_e32 v101, 0x3fb8aa3b, v65
	v_mul_f32_e32 v102, 0x3fb8aa3b, v66
	v_mul_f32_e32 v103, 0x3fb8aa3b, v67
	v_exp_f32_e32 v92, v92
	v_exp_f32_e32 v93, v93
	v_exp_f32_e32 v94, v94
	v_exp_f32_e32 v95, v95
	v_exp_f32_e32 v100, v100
	v_exp_f32_e32 v101, v101
	v_exp_f32_e32 v102, v102
	v_exp_f32_e32 v103, v103
	v_sub_f32_e32 v96, 1.0, v96
	v_sub_f32_e32 v97, 1.0, v97
	v_sub_f32_e32 v98, 1.0, v98
	v_sub_f32_e32 v99, 1.0, v99
	v_mul_f32_e32 v96, v96, v92
	v_mul_f32_e32 v97, v97, v93
	v_mul_f32_e32 v98, v98, v94
	v_mul_f32_e32 v99, v99, v95
	v_lshlrev_b32_e32 v92, 16, v34
	v_and_b32_e32 v93, 0xffff0000, v34
	v_lshlrev_b32_e32 v94, 16, v35
	v_and_b32_e32 v95, 0xffff0000, v35
	v_mul_f32_e32 v92, v92, v100
	v_mul_f32_e32 v93, v93, v101
	v_mul_f32_e32 v94, v94, v102
	v_mul_f32_e32 v95, v95, v103
	v_mov_b32_e32 v119, v96
	v_mov_b32_e32 v135, v97
	v_mov_b32_e32 v169, v98
	v_mov_b32_e32 v185, v99
	v_cvt_pk_bf16_f32 v92, v92, v93
	v_cvt_pk_bf16_f32 v93, v94, v95
	v_cvt_pk_bf16_f32 v96, v96, v97
	v_cvt_pk_bf16_f32 v97, v98, v99
	global_store_dwordx2 v112, v[92:93], s[2:3]
	global_store_dwordx2 v114, v[96:97], s[2:3]
	s_sub_u32 s2, s2, 0x400
	s_subb_u32 s3, s3, 0
	v_lshlrev_b32_e32 v92, 16, v36
	v_and_b32_e32 v93, 0xffff0000, v36
	v_lshlrev_b32_e32 v94, 16, v37
	v_and_b32_e32 v95, 0xffff0000, v37
	v_mul_f32_e32 v92, 0xbfb8aa3b, v92
	v_mul_f32_e32 v93, 0xbfb8aa3b, v93
	v_mul_f32_e32 v94, 0xbfb8aa3b, v94
	v_mul_f32_e32 v95, 0xbfb8aa3b, v95
	v_exp_f32_e32 v92, v92
	v_exp_f32_e32 v93, v93
	v_exp_f32_e32 v94, v94
	v_exp_f32_e32 v95, v95
	v_add_f32_e32 v92, 1.0, v92
	v_add_f32_e32 v93, 1.0, v93
	v_add_f32_e32 v94, 1.0, v94
	v_add_f32_e32 v95, 1.0, v95
	v_rcp_f32_e32 v92, v92
	v_rcp_f32_e32 v93, v93
	v_rcp_f32_e32 v94, v94
	v_rcp_f32_e32 v95, v95
	v_fma_f32 v96, v72, v92, v68
	v_fma_f32 v97, v73, v93, v69
	v_fma_f32 v98, v74, v94, v70
	v_fma_f32 v99, v75, v95, v71
	v_cmp_gt_f32_e64 s[22:23], s30, v96
	v_cmp_gt_f32_e64 s[24:25], s30, v97
	v_cmp_gt_f32_e64 s[26:27], s30, v98
	v_cmp_gt_f32_e64 s[28:29], s30, v99
	v_cndmask_b32_e64 v92, 0, 32, s[22:23]
	v_cndmask_b32_e64 v93, 0, 32, s[24:25]
	v_cndmask_b32_e64 v94, 0, 32, s[26:27]
	v_cndmask_b32_e64 v95, 0, 32, s[28:29]
	v_ldexp_f32 v92, v96, v92
	v_ldexp_f32 v93, v97, v93
	v_ldexp_f32 v94, v98, v94
	v_ldexp_f32 v95, v99, v95
	v_log_f32_e32 v92, v92
	v_log_f32_e32 v93, v93
	v_log_f32_e32 v94, v94
	v_log_f32_e32 v95, v95
	v_mul_f32_e32 v100, 0x3f317217, v92
	v_mul_f32_e32 v101, 0x3f317217, v93
	v_mul_f32_e32 v102, 0x3f317217, v94
	v_mul_f32_e32 v103, 0x3f317217, v95
	v_fma_f32 v100, v92, s31, -v100
	v_fma_f32 v101, v93, s31, -v101
	v_fma_f32 v102, v94, s31, -v102
	v_fma_f32 v103, v95, s31, -v103
	v_fmac_f32_e32 v100, 0x3377d1cf, v92
	v_fmac_f32_e32 v101, 0x3377d1cf, v93
	v_fmac_f32_e32 v102, 0x3377d1cf, v94
	v_fmac_f32_e32 v103, 0x3377d1cf, v95
	v_fmac_f32_e32 v100, 0x3f317217, v92
	v_fmac_f32_e32 v101, 0x3f317217, v93
	v_fmac_f32_e32 v102, 0x3f317217, v94
; DEV u16 f2bf(float f) { return (u16)(pack2(f, f) & 0xffffu); }
; DEV float bf2f(u16 h) { return __uint_as_float(((unsigned)h) << 16); }
; DEV float sigmoid_f(float x) { return __builtin_amdgcn_rcpf(1.f + __expf(-x)); }
; DEV void phase_p15(const Params& p, int g) {
;     ...
; #pragma unroll
;       for (int cc = 0; cc < 2; ++cc) {
;         const int c = tid + 256 * cc;
;         unsigned kb[8];
; #pragma unroll
;         for (int e = 0; e < 8; ++e) {
;           const int jj = j8 * 8 + e;
;           const int j = dir ? 63 - jj : jj;
;           const size_t tok = (size_t)cidx * 64 + j;
;           const float f = lb[cc] + (1.f - lb[cc]) * sigmoid_f(bf2f(xr[st][cc][e]));
;           G[cc] += __logf(f);
;           const float eg = __expf(G[cc]), ig = __expf(-G[cc]);
;           Qp[tok * 512 + c] = f2bf(bf2f(qr[st][cc][e]) * eg);
;           const u16 kk = f2bf((1.f - f) * ig);
;           Kp[tok * 512 + c] = kk;
;           kb[e] = kk;
;         }
;         const int s0 = dir ? 56 - 8 * j8 : 8 * j8;
;         uint4 w;
;         w.x = dir ? (kb[7] | (kb[6] << 16)) : (kb[0] | (kb[1] << 16));
;         w.y = dir ? (kb[5] | (kb[4] << 16)) : (kb[2] | (kb[3] << 16));
;         w.z = dir ? (kb[3] | (kb[2] << 16)) : (kb[4] | (kb[5] << 16));
;         w.w = dir ? (kb[1] | (kb[0] << 16)) : (kb[6] | (kb[7] << 16));
;         *(uint4*)(KT + (((size_t)cidx * 2 + dir) * 512 + c) * 64 + s0) = w;
;       }
	v_fmac_f32_e32 v103, 0x3f317217, v95
	v_cmp_lt_f32_e64 vcc, |v92|, s34
	v_cndmask_b32_e32 v92, v92, v100, vcc
	v_cmp_lt_f32_e64 vcc, |v93|, s34
	v_cndmask_b32_e32 v93, v93, v101, vcc
	v_cmp_lt_f32_e64 vcc, |v94|, s34
	v_cndmask_b32_e32 v94, v94, v102, vcc
	v_cmp_lt_f32_e64 vcc, |v95|, s34
	v_cndmask_b32_e32 v95, v95, v103, vcc
	v_cndmask_b32_e64 v100, 0, v213, s[22:23]
	v_cndmask_b32_e64 v101, 0, v213, s[24:25]
	v_cndmask_b32_e64 v102, 0, v213, s[26:27]
	v_cndmask_b32_e64 v103, 0, v213, s[28:29]
	v_sub_f32_e32 v92, v92, v100
	v_sub_f32_e32 v93, v93, v101
	v_sub_f32_e32 v94, v94, v102
	v_sub_f32_e32 v95, v95, v103
	v_add_f32_e32 v64, v64, v92
	v_add_f32_e32 v65, v65, v93
	v_add_f32_e32 v66, v66, v94
	v_add_f32_e32 v67, v67, v95
	v_mul_f32_e32 v92, 0xbfb8aa3b, v64
	v_mul_f32_e32 v93, 0xbfb8aa3b, v65
	v_mul_f32_e32 v94, 0xbfb8aa3b, v66
	v_mul_f32_e32 v95, 0xbfb8aa3b, v67
	v_mul_f32_e32 v100, 0x3fb8aa3b, v64
	v_mul_f32_e32 v101, 0x3fb8aa3b, v65
	v_mul_f32_e32 v102, 0x3fb8aa3b, v66
	v_mul_f32_e32 v103, 0x3fb8aa3b, v67
	v_exp_f32_e32 v92, v92
	v_exp_f32_e32 v93, v93
	v_exp_f32_e32 v94, v94
	v_exp_f32_e32 v95, v95
	v_exp_f32_e32 v100, v100
	v_exp_f32_e32 v101, v101
	v_exp_f32_e32 v102, v102
	v_exp_f32_e32 v103, v103
	v_sub_f32_e32 v96, 1.0, v96
	v_sub_f32_e32 v97, 1.0, v97
	v_sub_f32_e32 v98, 1.0, v98
	v_sub_f32_e32 v99, 1.0, v99
	v_mul_f32_e32 v96, v96, v92
	v_mul_f32_e32 v97, v97, v93
	v_mul_f32_e32 v98, v98, v94
	v_mul_f32_e32 v99, v99, v95
	v_lshlrev_b32_e32 v92, 16, v38
	v_and_b32_e32 v93, 0xffff0000, v38
	v_lshlrev_b32_e32 v94, 16, v39
	v_and_b32_e32 v95, 0xffff0000, v39
	v_mul_f32_e32 v92, v92, v100
	v_mul_f32_e32 v93, v93, v101
	v_mul_f32_e32 v94, v94, v102
	v_mul_f32_e32 v95, v95, v103
	v_cvt_pk_bf16_f32 v119, v96, v119
	v_cvt_pk_bf16_f32 v135, v97, v135
	v_cvt_pk_bf16_f32 v169, v98, v169
	v_cvt_pk_bf16_f32 v185, v99, v185
	v_cvt_pk_bf16_f32 v92, v92, v93
	v_cvt_pk_bf16_f32 v93, v94, v95
	v_cvt_pk_bf16_f32 v96, v96, v97
	v_cvt_pk_bf16_f32 v97, v98, v99
	global_store_dwordx2 v112, v[92:93], s[2:3]
	global_store_dwordx2 v114, v[96:97], s[2:3]
	s_sub_u32 s2, s2, 0x400
	s_subb_u32 s3, s3, 0
	v_lshlrev_b32_e32 v92, 16, v40
	v_and_b32_e32 v93, 0xffff0000, v40
	v_lshlrev_b32_e32 v94, 16, v41
	v_and_b32_e32 v95, 0xffff0000, v41
	v_mul_f32_e32 v92, 0xbfb8aa3b, v92
	v_mul_f32_e32 v93, 0xbfb8aa3b, v93
	v_mul_f32_e32 v94, 0xbfb8aa3b, v94
	v_mul_f32_e32 v95, 0xbfb8aa3b, v95
	v_exp_f32_e32 v92, v92
	v_exp_f32_e32 v93, v93
	v_exp_f32_e32 v94, v94
	v_exp_f32_e32 v95, v95
	v_add_f32_e32 v92, 1.0, v92
	v_add_f32_e32 v93, 1.0, v93
	v_add_f32_e32 v94, 1.0, v94
	v_add_f32_e32 v95, 1.0, v95
	v_rcp_f32_e32 v92, v92
	v_rcp_f32_e32 v93, v93
	v_rcp_f32_e32 v94, v94
	v_rcp_f32_e32 v95, v95
	v_fma_f32 v96, v72, v92, v68
	v_fma_f32 v97, v73, v93, v69
	v_fma_f32 v98, v74, v94, v70
	v_fma_f32 v99, v75, v95, v71
	v_cmp_gt_f32_e64 s[22:23], s30, v96
	v_cmp_gt_f32_e64 s[24:25], s30, v97
	v_cmp_gt_f32_e64 s[26:27], s30, v98
	v_cmp_gt_f32_e64 s[28:29], s30, v99
	v_cndmask_b32_e64 v92, 0, 32, s[22:23]
	v_cndmask_b32_e64 v93, 0, 32, s[24:25]
	v_cndmask_b32_e64 v94, 0, 32, s[26:27]
	v_cndmask_b32_e64 v95, 0, 32, s[28:29]
	v_ldexp_f32 v92, v96, v92
	v_ldexp_f32 v93, v97, v93
	v_ldexp_f32 v94, v98, v94
	v_ldexp_f32 v95, v99, v95
	v_log_f32_e32 v92, v92
	v_log_f32_e32 v93, v93
	v_log_f32_e32 v94, v94
	v_log_f32_e32 v95, v95
	v_mul_f32_e32 v100, 0x3f317217, v92
	v_mul_f32_e32 v101, 0x3f317217, v93
	v_mul_f32_e32 v102, 0x3f317217, v94
	v_mul_f32_e32 v103, 0x3f317217, v95
	v_fma_f32 v100, v92, s31, -v100
	v_fma_f32 v101, v93, s31, -v101
	v_fma_f32 v102, v94, s31, -v102
	v_fma_f32 v103, v95, s31, -v103
	v_fmac_f32_e32 v100, 0x3377d1cf, v92
	v_fmac_f32_e32 v101, 0x3377d1cf, v93
	v_fmac_f32_e32 v102, 0x3377d1cf, v94
	v_fmac_f32_e32 v103, 0x3377d1cf, v95
	v_fmac_f32_e32 v100, 0x3f317217, v92
	v_fmac_f32_e32 v101, 0x3f317217, v93
	v_fmac_f32_e32 v102, 0x3f317217, v94
	v_fmac_f32_e32 v103, 0x3f317217, v95
	v_cmp_lt_f32_e64 vcc, |v92|, s34
	v_cndmask_b32_e32 v92, v92, v100, vcc
	v_cmp_lt_f32_e64 vcc, |v93|, s34
	v_cndmask_b32_e32 v93, v93, v101, vcc
	v_cmp_lt_f32_e64 vcc, |v94|, s34
	v_cndmask_b32_e32 v94, v94, v102, vcc
	v_cmp_lt_f32_e64 vcc, |v95|, s34
	v_cndmask_b32_e32 v95, v95, v103, vcc
	v_cndmask_b32_e64 v100, 0, v213, s[22:23]
	v_cndmask_b32_e64 v101, 0, v213, s[24:25]
	v_cndmask_b32_e64 v102, 0, v213, s[26:27]
	v_cndmask_b32_e64 v103, 0, v213, s[28:29]
	v_sub_f32_e32 v92, v92, v100
	v_sub_f32_e32 v93, v93, v101
	v_sub_f32_e32 v94, v94, v102
	v_sub_f32_e32 v95, v95, v103
	v_add_f32_e32 v64, v64, v92
	v_add_f32_e32 v65, v65, v93
	v_add_f32_e32 v66, v66, v94
	v_add_f32_e32 v67, v67, v95
	v_mul_f32_e32 v92, 0xbfb8aa3b, v64
	v_mul_f32_e32 v93, 0xbfb8aa3b, v65
	v_mul_f32_e32 v94, 0xbfb8aa3b, v66
	v_mul_f32_e32 v95, 0xbfb8aa3b, v67
	v_mul_f32_e32 v100, 0x3fb8aa3b, v64
	v_mul_f32_e32 v101, 0x3fb8aa3b, v65
	v_mul_f32_e32 v102, 0x3fb8aa3b, v66
	v_mul_f32_e32 v103, 0x3fb8aa3b, v67
	v_exp_f32_e32 v92, v92
	v_exp_f32_e32 v93, v93
	v_exp_f32_e32 v94, v94
	v_exp_f32_e32 v95, v95
	v_exp_f32_e32 v100, v100
	v_exp_f32_e32 v101, v101
	v_exp_f32_e32 v102, v102
	v_exp_f32_e32 v103, v103
	v_sub_f32_e32 v96, 1.0, v96
	v_sub_f32_e32 v97, 1.0, v97
	v_sub_f32_e32 v98, 1.0, v98
	v_sub_f32_e32 v99, 1.0, v99
	v_mul_f32_e32 v96, v96, v92
	v_mul_f32_e32 v97, v97, v93
	v_mul_f32_e32 v98, v98, v94
	v_mul_f32_e32 v99, v99, v95
	v_lshlrev_b32_e32 v92, 16, v42
	v_and_b32_e32 v93, 0xffff0000, v42
	v_lshlrev_b32_e32 v94, 16, v43
	v_and_b32_e32 v95, 0xffff0000, v43
	v_mul_f32_e32 v92, v92, v100
	v_mul_f32_e32 v93, v93, v101
	v_mul_f32_e32 v94, v94, v102
	v_mul_f32_e32 v95, v95, v103
	v_mov_b32_e32 v118, v96
; DEV u16 f2bf(float f) { return (u16)(pack2(f, f) & 0xffffu); }
; DEV float bf2f(u16 h) { return __uint_as_float(((unsigned)h) << 16); }
; DEV float sigmoid_f(float x) { return __builtin_amdgcn_rcpf(1.f + __expf(-x)); }
; DEV void phase_p15(const Params& p, int g) {
;     ...
; #pragma unroll
;       for (int cc = 0; cc < 2; ++cc) {
;         const int c = tid + 256 * cc;
;         unsigned kb[8];
; #pragma unroll
;         for (int e = 0; e < 8; ++e) {
;           const int jj = j8 * 8 + e;
;           const int j = dir ? 63 - jj : jj;
;           const size_t tok = (size_t)cidx * 64 + j;
;           const float f = lb[cc] + (1.f - lb[cc]) * sigmoid_f(bf2f(xr[st][cc][e]));
;           G[cc] += __logf(f);
;           const float eg = __expf(G[cc]), ig = __expf(-G[cc]);
;           Qp[tok * 512 + c] = f2bf(bf2f(qr[st][cc][e]) * eg);
;           const u16 kk = f2bf((1.f - f) * ig);
;           Kp[tok * 512 + c] = kk;
;           kb[e] = kk;
;         }
;         const int s0 = dir ? 56 - 8 * j8 : 8 * j8;
;         uint4 w;
;         w.x = dir ? (kb[7] | (kb[6] << 16)) : (kb[0] | (kb[1] << 16));
;         w.y = dir ? (kb[5] | (kb[4] << 16)) : (kb[2] | (kb[3] << 16));
;         w.z = dir ? (kb[3] | (kb[2] << 16)) : (kb[4] | (kb[5] << 16));
;         w.w = dir ? (kb[1] | (kb[0] << 16)) : (kb[6] | (kb[7] << 16));
;         *(uint4*)(KT + (((size_t)cidx * 2 + dir) * 512 + c) * 64 + s0) = w;
;       }
	v_mov_b32_e32 v134, v97
	v_mov_b32_e32 v168, v98
	v_mov_b32_e32 v184, v99
	v_cvt_pk_bf16_f32 v92, v92, v93
	v_cvt_pk_bf16_f32 v93, v94, v95
	v_cvt_pk_bf16_f32 v96, v96, v97
	v_cvt_pk_bf16_f32 v97, v98, v99
	global_store_dwordx2 v112, v[92:93], s[2:3]
	global_store_dwordx2 v114, v[96:97], s[2:3]
	s_sub_u32 s2, s2, 0x400
	s_subb_u32 s3, s3, 0
	v_lshlrev_b32_e32 v92, 16, v44
	v_and_b32_e32 v93, 0xffff0000, v44
	v_lshlrev_b32_e32 v94, 16, v45
	v_and_b32_e32 v95, 0xffff0000, v45
	v_mul_f32_e32 v92, 0xbfb8aa3b, v92
	v_mul_f32_e32 v93, 0xbfb8aa3b, v93
	v_mul_f32_e32 v94, 0xbfb8aa3b, v94
	v_mul_f32_e32 v95, 0xbfb8aa3b, v95
	v_exp_f32_e32 v92, v92
	v_exp_f32_e32 v93, v93
	v_exp_f32_e32 v94, v94
	v_exp_f32_e32 v95, v95
	v_add_f32_e32 v92, 1.0, v92
	v_add_f32_e32 v93, 1.0, v93
	v_add_f32_e32 v94, 1.0, v94
	v_add_f32_e32 v95, 1.0, v95
	v_rcp_f32_e32 v92, v92
	v_rcp_f32_e32 v93, v93
	v_rcp_f32_e32 v94, v94
	v_rcp_f32_e32 v95, v95
	v_fma_f32 v96, v72, v92, v68
	v_fma_f32 v97, v73, v93, v69
	v_fma_f32 v98, v74, v94, v70
	v_fma_f32 v99, v75, v95, v71
	v_cmp_gt_f32_e64 s[22:23], s30, v96
	v_cmp_gt_f32_e64 s[24:25], s30, v97
	v_cmp_gt_f32_e64 s[26:27], s30, v98
	v_cmp_gt_f32_e64 s[28:29], s30, v99
	v_cndmask_b32_e64 v92, 0, 32, s[22:23]
	v_cndmask_b32_e64 v93, 0, 32, s[24:25]
	v_cndmask_b32_e64 v94, 0, 32, s[26:27]
	v_cndmask_b32_e64 v95, 0, 32, s[28:29]
	v_ldexp_f32 v92, v96, v92
	v_ldexp_f32 v93, v97, v93
	v_ldexp_f32 v94, v98, v94
	v_ldexp_f32 v95, v99, v95
	v_log_f32_e32 v92, v92
	v_log_f32_e32 v93, v93
	v_log_f32_e32 v94, v94
	v_log_f32_e32 v95, v95
	v_mul_f32_e32 v100, 0x3f317217, v92
	v_mul_f32_e32 v101, 0x3f317217, v93
	v_mul_f32_e32 v102, 0x3f317217, v94
	v_mul_f32_e32 v103, 0x3f317217, v95
	v_fma_f32 v100, v92, s31, -v100
	v_fma_f32 v101, v93, s31, -v101
	v_fma_f32 v102, v94, s31, -v102
	v_fma_f32 v103, v95, s31, -v103
	v_fmac_f32_e32 v100, 0x3377d1cf, v92
	v_fmac_f32_e32 v101, 0x3377d1cf, v93
	v_fmac_f32_e32 v102, 0x3377d1cf, v94
	v_fmac_f32_e32 v103, 0x3377d1cf, v95
	v_fmac_f32_e32 v100, 0x3f317217, v92
	v_fmac_f32_e32 v101, 0x3f317217, v93
	v_fmac_f32_e32 v102, 0x3f317217, v94
	v_fmac_f32_e32 v103, 0x3f317217, v95
	v_cmp_lt_f32_e64 vcc, |v92|, s34
	v_cndmask_b32_e32 v92, v92, v100, vcc
	v_cmp_lt_f32_e64 vcc, |v93|, s34
	v_cndmask_b32_e32 v93, v93, v101, vcc
	v_cmp_lt_f32_e64 vcc, |v94|, s34
	v_cndmask_b32_e32 v94, v94, v102, vcc
	v_cmp_lt_f32_e64 vcc, |v95|, s34
	v_cndmask_b32_e32 v95, v95, v103, vcc
	v_cndmask_b32_e64 v100, 0, v213, s[22:23]
	v_cndmask_b32_e64 v101, 0, v213, s[24:25]
	v_cndmask_b32_e64 v102, 0, v213, s[26:27]
	v_cndmask_b32_e64 v103, 0, v213, s[28:29]
	v_sub_f32_e32 v92, v92, v100
	v_sub_f32_e32 v93, v93, v101
	v_sub_f32_e32 v94, v94, v102
	v_sub_f32_e32 v95, v95, v103
	v_add_f32_e32 v64, v64, v92
	v_add_f32_e32 v65, v65, v93
	v_add_f32_e32 v66, v66, v94
	v_add_f32_e32 v67, v67, v95
	v_mul_f32_e32 v92, 0xbfb8aa3b, v64
	v_mul_f32_e32 v93, 0xbfb8aa3b, v65
	v_mul_f32_e32 v94, 0xbfb8aa3b, v66
	v_mul_f32_e32 v95, 0xbfb8aa3b, v67
	v_mul_f32_e32 v100, 0x3fb8aa3b, v64
	v_mul_f32_e32 v101, 0x3fb8aa3b, v65
	v_mul_f32_e32 v102, 0x3fb8aa3b, v66
	v_mul_f32_e32 v103, 0x3fb8aa3b, v67
	v_exp_f32_e32 v92, v92
	v_exp_f32_e32 v93, v93
	v_exp_f32_e32 v94, v94
	v_exp_f32_e32 v95, v95
	v_exp_f32_e32 v100, v100
	v_exp_f32_e32 v101, v101
	v_exp_f32_e32 v102, v102
	v_exp_f32_e32 v103, v103
	v_sub_f32_e32 v96, 1.0, v96
	v_sub_f32_e32 v97, 1.0, v97
	v_sub_f32_e32 v98, 1.0, v98
	v_sub_f32_e32 v99, 1.0, v99
	v_mul_f32_e32 v96, v96, v92
	v_mul_f32_e32 v97, v97, v93
	v_mul_f32_e32 v98, v98, v94
	v_mul_f32_e32 v99, v99, v95
	v_lshlrev_b32_e32 v92, 16, v46
	v_and_b32_e32 v93, 0xffff0000, v46
	v_lshlrev_b32_e32 v94, 16, v47
	v_and_b32_e32 v95, 0xffff0000, v47
	v_mul_f32_e32 v92, v92, v100
	v_mul_f32_e32 v93, v93, v101
	v_mul_f32_e32 v94, v94, v102
	v_mul_f32_e32 v95, v95, v103
	v_cvt_pk_bf16_f32 v118, v96, v118
	v_cvt_pk_bf16_f32 v134, v97, v134
	v_cvt_pk_bf16_f32 v168, v98, v168
	v_cvt_pk_bf16_f32 v184, v99, v184
	v_cvt_pk_bf16_f32 v92, v92, v93
	v_cvt_pk_bf16_f32 v93, v94, v95
	v_cvt_pk_bf16_f32 v96, v96, v97
	v_cvt_pk_bf16_f32 v97, v98, v99
	global_store_dwordx2 v112, v[92:93], s[2:3]
	global_store_dwordx2 v114, v[96:97], s[2:3]
	s_sub_u32 s2, s2, 0x400
	s_subb_u32 s3, s3, 0
	v_lshlrev_b32_e32 v92, 16, v48
	v_and_b32_e32 v93, 0xffff0000, v48
	v_lshlrev_b32_e32 v94, 16, v49
	v_and_b32_e32 v95, 0xffff0000, v49
	v_mul_f32_e32 v92, 0xbfb8aa3b, v92
	v_mul_f32_e32 v93, 0xbfb8aa3b, v93
	v_mul_f32_e32 v94, 0xbfb8aa3b, v94
	v_mul_f32_e32 v95, 0xbfb8aa3b, v95
	v_exp_f32_e32 v92, v92
	v_exp_f32_e32 v93, v93
	v_exp_f32_e32 v94, v94
	v_exp_f32_e32 v95, v95
	v_add_f32_e32 v92, 1.0, v92
	v_add_f32_e32 v93, 1.0, v93
	v_add_f32_e32 v94, 1.0, v94
	v_add_f32_e32 v95, 1.0, v95
	v_rcp_f32_e32 v92, v92
	v_rcp_f32_e32 v93, v93
	v_rcp_f32_e32 v94, v94
	v_rcp_f32_e32 v95, v95
	v_fma_f32 v96, v72, v92, v68
	v_fma_f32 v97, v73, v93, v69
	v_fma_f32 v98, v74, v94, v70
	v_fma_f32 v99, v75, v95, v71
	v_cmp_gt_f32_e64 s[22:23], s30, v96
	v_cmp_gt_f32_e64 s[24:25], s30, v97
	v_cmp_gt_f32_e64 s[26:27], s30, v98
	v_cmp_gt_f32_e64 s[28:29], s30, v99
	v_cndmask_b32_e64 v92, 0, 32, s[22:23]
	v_cndmask_b32_e64 v93, 0, 32, s[24:25]
	v_cndmask_b32_e64 v94, 0, 32, s[26:27]
	v_cndmask_b32_e64 v95, 0, 32, s[28:29]
	v_ldexp_f32 v92, v96, v92
	v_ldexp_f32 v93, v97, v93
	v_ldexp_f32 v94, v98, v94
	v_ldexp_f32 v95, v99, v95
	v_log_f32_e32 v92, v92
	v_log_f32_e32 v93, v93
	v_log_f32_e32 v94, v94
	v_log_f32_e32 v95, v95
	v_mul_f32_e32 v100, 0x3f317217, v92
	v_mul_f32_e32 v101, 0x3f317217, v93
	v_mul_f32_e32 v102, 0x3f317217, v94
	v_mul_f32_e32 v103, 0x3f317217, v95
	v_fma_f32 v100, v92, s31, -v100
; DEV u16 f2bf(float f) { return (u16)(pack2(f, f) & 0xffffu); }
; DEV float bf2f(u16 h) { return __uint_as_float(((unsigned)h) << 16); }
; DEV float sigmoid_f(float x) { return __builtin_amdgcn_rcpf(1.f + __expf(-x)); }
; DEV void phase_p15(const Params& p, int g) {
;     ...
; #pragma unroll
;       for (int cc = 0; cc < 2; ++cc) {
;         const int c = tid + 256 * cc;
;         unsigned kb[8];
; #pragma unroll
;         for (int e = 0; e < 8; ++e) {
;           const int jj = j8 * 8 + e;
;           const int j = dir ? 63 - jj : jj;
;           const size_t tok = (size_t)cidx * 64 + j;
;           const float f = lb[cc] + (1.f - lb[cc]) * sigmoid_f(bf2f(xr[st][cc][e]));
;           G[cc] += __logf(f);
;           const float eg = __expf(G[cc]), ig = __expf(-G[cc]);
;           Qp[tok * 512 + c] = f2bf(bf2f(qr[st][cc][e]) * eg);
;           const u16 kk = f2bf((1.f - f) * ig);
;           Kp[tok * 512 + c] = kk;
;           kb[e] = kk;
;         }
;         const int s0 = dir ? 56 - 8 * j8 : 8 * j8;
;         uint4 w;
;         w.x = dir ? (kb[7] | (kb[6] << 16)) : (kb[0] | (kb[1] << 16));
;         w.y = dir ? (kb[5] | (kb[4] << 16)) : (kb[2] | (kb[3] << 16));
;         w.z = dir ? (kb[3] | (kb[2] << 16)) : (kb[4] | (kb[5] << 16));
;         w.w = dir ? (kb[1] | (kb[0] << 16)) : (kb[6] | (kb[7] << 16));
;         *(uint4*)(KT + (((size_t)cidx * 2 + dir) * 512 + c) * 64 + s0) = w;
;       }
	v_fma_f32 v101, v93, s31, -v101
	v_fma_f32 v102, v94, s31, -v102
	v_fma_f32 v103, v95, s31, -v103
	v_fmac_f32_e32 v100, 0x3377d1cf, v92
	v_fmac_f32_e32 v101, 0x3377d1cf, v93
	v_fmac_f32_e32 v102, 0x3377d1cf, v94
	v_fmac_f32_e32 v103, 0x3377d1cf, v95
	v_fmac_f32_e32 v100, 0x3f317217, v92
	v_fmac_f32_e32 v101, 0x3f317217, v93
	v_fmac_f32_e32 v102, 0x3f317217, v94
	v_fmac_f32_e32 v103, 0x3f317217, v95
	v_cmp_lt_f32_e64 vcc, |v92|, s34
	v_cndmask_b32_e32 v92, v92, v100, vcc
	v_cmp_lt_f32_e64 vcc, |v93|, s34
	v_cndmask_b32_e32 v93, v93, v101, vcc
	v_cmp_lt_f32_e64 vcc, |v94|, s34
	v_cndmask_b32_e32 v94, v94, v102, vcc
	v_cmp_lt_f32_e64 vcc, |v95|, s34
	v_cndmask_b32_e32 v95, v95, v103, vcc
	v_cndmask_b32_e64 v100, 0, v213, s[22:23]
	v_cndmask_b32_e64 v101, 0, v213, s[24:25]
	v_cndmask_b32_e64 v102, 0, v213, s[26:27]
	v_cndmask_b32_e64 v103, 0, v213, s[28:29]
	v_sub_f32_e32 v92, v92, v100
	v_sub_f32_e32 v93, v93, v101
	v_sub_f32_e32 v94, v94, v102
	v_sub_f32_e32 v95, v95, v103
	v_add_f32_e32 v64, v64, v92
	v_add_f32_e32 v65, v65, v93
	v_add_f32_e32 v66, v66, v94
	v_add_f32_e32 v67, v67, v95
	v_mul_f32_e32 v92, 0xbfb8aa3b, v64
	v_mul_f32_e32 v93, 0xbfb8aa3b, v65
	v_mul_f32_e32 v94, 0xbfb8aa3b, v66
	v_mul_f32_e32 v95, 0xbfb8aa3b, v67
	v_mul_f32_e32 v100, 0x3fb8aa3b, v64
	v_mul_f32_e32 v101, 0x3fb8aa3b, v65
	v_mul_f32_e32 v102, 0x3fb8aa3b, v66
	v_mul_f32_e32 v103, 0x3fb8aa3b, v67
	v_exp_f32_e32 v92, v92
	v_exp_f32_e32 v93, v93
	v_exp_f32_e32 v94, v94
	v_exp_f32_e32 v95, v95
	v_exp_f32_e32 v100, v100
	v_exp_f32_e32 v101, v101
	v_exp_f32_e32 v102, v102
	v_exp_f32_e32 v103, v103
	v_sub_f32_e32 v96, 1.0, v96
	v_sub_f32_e32 v97, 1.0, v97
	v_sub_f32_e32 v98, 1.0, v98
	v_sub_f32_e32 v99, 1.0, v99
	v_mul_f32_e32 v96, v96, v92
	v_mul_f32_e32 v97, v97, v93
	v_mul_f32_e32 v98, v98, v94
	v_mul_f32_e32 v99, v99, v95
	v_lshlrev_b32_e32 v92, 16, v50
	v_and_b32_e32 v93, 0xffff0000, v50
	v_lshlrev_b32_e32 v94, 16, v51
	v_and_b32_e32 v95, 0xffff0000, v51
	v_mul_f32_e32 v92, v92, v100
	v_mul_f32_e32 v93, v93, v101
	v_mul_f32_e32 v94, v94, v102
	v_mul_f32_e32 v95, v95, v103
	v_mov_b32_e32 v117, v96
	v_mov_b32_e32 v133, v97
	v_mov_b32_e32 v167, v98
	v_mov_b32_e32 v183, v99
	v_cvt_pk_bf16_f32 v92, v92, v93
	v_cvt_pk_bf16_f32 v93, v94, v95
	v_cvt_pk_bf16_f32 v96, v96, v97
	v_cvt_pk_bf16_f32 v97, v98, v99
	global_store_dwordx2 v112, v[92:93], s[2:3]
	global_store_dwordx2 v114, v[96:97], s[2:3]
	s_sub_u32 s2, s2, 0x400
	s_subb_u32 s3, s3, 0
	v_lshlrev_b32_e32 v92, 16, v52
	v_and_b32_e32 v93, 0xffff0000, v52
	v_lshlrev_b32_e32 v94, 16, v53
	v_and_b32_e32 v95, 0xffff0000, v53
	v_mul_f32_e32 v92, 0xbfb8aa3b, v92
	v_mul_f32_e32 v93, 0xbfb8aa3b, v93
	v_mul_f32_e32 v94, 0xbfb8aa3b, v94
	v_mul_f32_e32 v95, 0xbfb8aa3b, v95
	v_exp_f32_e32 v92, v92
	v_exp_f32_e32 v93, v93
	v_exp_f32_e32 v94, v94
	v_exp_f32_e32 v95, v95
	v_add_f32_e32 v92, 1.0, v92
	v_add_f32_e32 v93, 1.0, v93
	v_add_f32_e32 v94, 1.0, v94
	v_add_f32_e32 v95, 1.0, v95
	v_rcp_f32_e32 v92, v92
	v_rcp_f32_e32 v93, v93
	v_rcp_f32_e32 v94, v94
	v_rcp_f32_e32 v95, v95
	v_fma_f32 v96, v72, v92, v68
	v_fma_f32 v97, v73, v93, v69
	v_fma_f32 v98, v74, v94, v70
	v_fma_f32 v99, v75, v95, v71
	v_cmp_gt_f32_e64 s[22:23], s30, v96
	v_cmp_gt_f32_e64 s[24:25], s30, v97
	v_cmp_gt_f32_e64 s[26:27], s30, v98
	v_cmp_gt_f32_e64 s[28:29], s30, v99
	v_cndmask_b32_e64 v92, 0, 32, s[22:23]
	v_cndmask_b32_e64 v93, 0, 32, s[24:25]
	v_cndmask_b32_e64 v94, 0, 32, s[26:27]
	v_cndmask_b32_e64 v95, 0, 32, s[28:29]
	v_ldexp_f32 v92, v96, v92
	v_ldexp_f32 v93, v97, v93
	v_ldexp_f32 v94, v98, v94
	v_ldexp_f32 v95, v99, v95
	v_log_f32_e32 v92, v92
	v_log_f32_e32 v93, v93
	v_log_f32_e32 v94, v94
	v_log_f32_e32 v95, v95
	v_mul_f32_e32 v100, 0x3f317217, v92
	v_mul_f32_e32 v101, 0x3f317217, v93
	v_mul_f32_e32 v102, 0x3f317217, v94
	v_mul_f32_e32 v103, 0x3f317217, v95
	v_fma_f32 v100, v92, s31, -v100
	v_fma_f32 v101, v93, s31, -v101
	v_fma_f32 v102, v94, s31, -v102
	v_fma_f32 v103, v95, s31, -v103
	v_fmac_f32_e32 v100, 0x3377d1cf, v92
	v_fmac_f32_e32 v101, 0x3377d1cf, v93
	v_fmac_f32_e32 v102, 0x3377d1cf, v94
	v_fmac_f32_e32 v103, 0x3377d1cf, v95
	v_fmac_f32_e32 v100, 0x3f317217, v92
	v_fmac_f32_e32 v101, 0x3f317217, v93
	v_fmac_f32_e32 v102, 0x3f317217, v94
	v_fmac_f32_e32 v103, 0x3f317217, v95
	v_cmp_lt_f32_e64 vcc, |v92|, s34
	v_cndmask_b32_e32 v92, v92, v100, vcc
	v_cmp_lt_f32_e64 vcc, |v93|, s34
	v_cndmask_b32_e32 v93, v93, v101, vcc
	v_cmp_lt_f32_e64 vcc, |v94|, s34
	v_cndmask_b32_e32 v94, v94, v102, vcc
	v_cmp_lt_f32_e64 vcc, |v95|, s34
	v_cndmask_b32_e32 v95, v95, v103, vcc
	v_cndmask_b32_e64 v100, 0, v213, s[22:23]
	v_cndmask_b32_e64 v101, 0, v213, s[24:25]
	v_cndmask_b32_e64 v102, 0, v213, s[26:27]
	v_cndmask_b32_e64 v103, 0, v213, s[28:29]
	v_sub_f32_e32 v92, v92, v100
	v_sub_f32_e32 v93, v93, v101
	v_sub_f32_e32 v94, v94, v102
	v_sub_f32_e32 v95, v95, v103
	v_add_f32_e32 v64, v64, v92
	v_add_f32_e32 v65, v65, v93
	v_add_f32_e32 v66, v66, v94
	v_add_f32_e32 v67, v67, v95
	v_mul_f32_e32 v92, 0xbfb8aa3b, v64
	v_mul_f32_e32 v93, 0xbfb8aa3b, v65
	v_mul_f32_e32 v94, 0xbfb8aa3b, v66
	v_mul_f32_e32 v95, 0xbfb8aa3b, v67
	v_mul_f32_e32 v100, 0x3fb8aa3b, v64
	v_mul_f32_e32 v101, 0x3fb8aa3b, v65
	v_mul_f32_e32 v102, 0x3fb8aa3b, v66
	v_mul_f32_e32 v103, 0x3fb8aa3b, v67
	v_exp_f32_e32 v92, v92
	v_exp_f32_e32 v93, v93
	v_exp_f32_e32 v94, v94
	v_exp_f32_e32 v95, v95
	v_exp_f32_e32 v100, v100
	v_exp_f32_e32 v101, v101
	v_exp_f32_e32 v102, v102
	v_exp_f32_e32 v103, v103
	v_sub_f32_e32 v96, 1.0, v96
	v_sub_f32_e32 v97, 1.0, v97
	v_sub_f32_e32 v98, 1.0, v98
	v_sub_f32_e32 v99, 1.0, v99
	v_mul_f32_e32 v96, v96, v92
	v_mul_f32_e32 v97, v97, v93
	v_mul_f32_e32 v98, v98, v94
; DEV u16 f2bf(float f) { return (u16)(pack2(f, f) & 0xffffu); }
; DEV float bf2f(u16 h) { return __uint_as_float(((unsigned)h) << 16); }
; DEV float sigmoid_f(float x) { return __builtin_amdgcn_rcpf(1.f + __expf(-x)); }
; DEV void phase_p15(const Params& p, int g) {
;     ...
; #pragma unroll
;       for (int cc = 0; cc < 2; ++cc) {
;         const int c = tid + 256 * cc;
;         unsigned kb[8];
; #pragma unroll
;         for (int e = 0; e < 8; ++e) {
;           const int jj = j8 * 8 + e;
;           const int j = dir ? 63 - jj : jj;
;           const size_t tok = (size_t)cidx * 64 + j;
;           const float f = lb[cc] + (1.f - lb[cc]) * sigmoid_f(bf2f(xr[st][cc][e]));
;           G[cc] += __logf(f);
;           const float eg = __expf(G[cc]), ig = __expf(-G[cc]);
;           Qp[tok * 512 + c] = f2bf(bf2f(qr[st][cc][e]) * eg);
;           const u16 kk = f2bf((1.f - f) * ig);
;           Kp[tok * 512 + c] = kk;
;           kb[e] = kk;
;         }
;         const int s0 = dir ? 56 - 8 * j8 : 8 * j8;
;         uint4 w;
;         w.x = dir ? (kb[7] | (kb[6] << 16)) : (kb[0] | (kb[1] << 16));
;         w.y = dir ? (kb[5] | (kb[4] << 16)) : (kb[2] | (kb[3] << 16));
;         w.z = dir ? (kb[3] | (kb[2] << 16)) : (kb[4] | (kb[5] << 16));
;         w.w = dir ? (kb[1] | (kb[0] << 16)) : (kb[6] | (kb[7] << 16));
;         *(uint4*)(KT + (((size_t)cidx * 2 + dir) * 512 + c) * 64 + s0) = w;
;       }
	v_mul_f32_e32 v99, v99, v95
	v_lshlrev_b32_e32 v92, 16, v54
	v_and_b32_e32 v93, 0xffff0000, v54
	v_lshlrev_b32_e32 v94, 16, v55
	v_and_b32_e32 v95, 0xffff0000, v55
	v_mul_f32_e32 v92, v92, v100
	v_mul_f32_e32 v93, v93, v101
	v_mul_f32_e32 v94, v94, v102
	v_mul_f32_e32 v95, v95, v103
	v_cvt_pk_bf16_f32 v117, v96, v117
	v_cvt_pk_bf16_f32 v133, v97, v133
	v_cvt_pk_bf16_f32 v167, v98, v167
	v_cvt_pk_bf16_f32 v183, v99, v183
	v_cvt_pk_bf16_f32 v92, v92, v93
	v_cvt_pk_bf16_f32 v93, v94, v95
	v_cvt_pk_bf16_f32 v96, v96, v97
	v_cvt_pk_bf16_f32 v97, v98, v99
	global_store_dwordx2 v112, v[92:93], s[2:3]
	global_store_dwordx2 v114, v[96:97], s[2:3]
	s_sub_u32 s2, s2, 0x400
	s_subb_u32 s3, s3, 0
	v_lshlrev_b32_e32 v92, 16, v56
	v_and_b32_e32 v93, 0xffff0000, v56
	v_lshlrev_b32_e32 v94, 16, v57
	v_and_b32_e32 v95, 0xffff0000, v57
	v_mul_f32_e32 v92, 0xbfb8aa3b, v92
	v_mul_f32_e32 v93, 0xbfb8aa3b, v93
	v_mul_f32_e32 v94, 0xbfb8aa3b, v94
	v_mul_f32_e32 v95, 0xbfb8aa3b, v95
	v_exp_f32_e32 v92, v92
	v_exp_f32_e32 v93, v93
	v_exp_f32_e32 v94, v94
	v_exp_f32_e32 v95, v95
	v_add_f32_e32 v92, 1.0, v92
	v_add_f32_e32 v93, 1.0, v93
	v_add_f32_e32 v94, 1.0, v94
	v_add_f32_e32 v95, 1.0, v95
	v_rcp_f32_e32 v92, v92
	v_rcp_f32_e32 v93, v93
	v_rcp_f32_e32 v94, v94
	v_rcp_f32_e32 v95, v95
	v_fma_f32 v96, v72, v92, v68
	v_fma_f32 v97, v73, v93, v69
	v_fma_f32 v98, v74, v94, v70
	v_fma_f32 v99, v75, v95, v71
	v_cmp_gt_f32_e64 s[22:23], s30, v96
	v_cmp_gt_f32_e64 s[24:25], s30, v97
	v_cmp_gt_f32_e64 s[26:27], s30, v98
	v_cmp_gt_f32_e64 s[28:29], s30, v99
	v_cndmask_b32_e64 v92, 0, 32, s[22:23]
	v_cndmask_b32_e64 v93, 0, 32, s[24:25]
	v_cndmask_b32_e64 v94, 0, 32, s[26:27]
	v_cndmask_b32_e64 v95, 0, 32, s[28:29]
	v_ldexp_f32 v92, v96, v92
	v_ldexp_f32 v93, v97, v93
	v_ldexp_f32 v94, v98, v94
	v_ldexp_f32 v95, v99, v95
	v_log_f32_e32 v92, v92
	v_log_f32_e32 v93, v93
	v_log_f32_e32 v94, v94
	v_log_f32_e32 v95, v95
	v_mul_f32_e32 v100, 0x3f317217, v92
	v_mul_f32_e32 v101, 0x3f317217, v93
	v_mul_f32_e32 v102, 0x3f317217, v94
	v_mul_f32_e32 v103, 0x3f317217, v95
	v_fma_f32 v100, v92, s31, -v100
	v_fma_f32 v101, v93, s31, -v101
	v_fma_f32 v102, v94, s31, -v102
	v_fma_f32 v103, v95, s31, -v103
	v_fmac_f32_e32 v100, 0x3377d1cf, v92
	v_fmac_f32_e32 v101, 0x3377d1cf, v93
	v_fmac_f32_e32 v102, 0x3377d1cf, v94
	v_fmac_f32_e32 v103, 0x3377d1cf, v95
	v_fmac_f32_e32 v100, 0x3f317217, v92
	v_fmac_f32_e32 v101, 0x3f317217, v93
	v_fmac_f32_e32 v102, 0x3f317217, v94
	v_fmac_f32_e32 v103, 0x3f317217, v95
	v_cmp_lt_f32_e64 vcc, |v92|, s34
	v_cndmask_b32_e32 v92, v92, v100, vcc
	v_cmp_lt_f32_e64 vcc, |v93|, s34
	v_cndmask_b32_e32 v93, v93, v101, vcc
	v_cmp_lt_f32_e64 vcc, |v94|, s34
	v_cndmask_b32_e32 v94, v94, v102, vcc
	v_cmp_lt_f32_e64 vcc, |v95|, s34
	v_cndmask_b32_e32 v95, v95, v103, vcc
	v_cndmask_b32_e64 v100, 0, v213, s[22:23]
	v_cndmask_b32_e64 v101, 0, v213, s[24:25]
	v_cndmask_b32_e64 v102, 0, v213, s[26:27]
	v_cndmask_b32_e64 v103, 0, v213, s[28:29]
	v_sub_f32_e32 v92, v92, v100
	v_sub_f32_e32 v93, v93, v101
	v_sub_f32_e32 v94, v94, v102
	v_sub_f32_e32 v95, v95, v103
	v_add_f32_e32 v64, v64, v92
	v_add_f32_e32 v65, v65, v93
	v_add_f32_e32 v66, v66, v94
	v_add_f32_e32 v67, v67, v95
	v_mul_f32_e32 v92, 0xbfb8aa3b, v64
	v_mul_f32_e32 v93, 0xbfb8aa3b, v65
	v_mul_f32_e32 v94, 0xbfb8aa3b, v66
	v_mul_f32_e32 v95, 0xbfb8aa3b, v67
	v_mul_f32_e32 v100, 0x3fb8aa3b, v64
	v_mul_f32_e32 v101, 0x3fb8aa3b, v65
	v_mul_f32_e32 v102, 0x3fb8aa3b, v66
	v_mul_f32_e32 v103, 0x3fb8aa3b, v67
	v_exp_f32_e32 v92, v92
	v_exp_f32_e32 v93, v93
	v_exp_f32_e32 v94, v94
	v_exp_f32_e32 v95, v95
	v_exp_f32_e32 v100, v100
	v_exp_f32_e32 v101, v101
	v_exp_f32_e32 v102, v102
	v_exp_f32_e32 v103, v103
	v_sub_f32_e32 v96, 1.0, v96
	v_sub_f32_e32 v97, 1.0, v97
	v_sub_f32_e32 v98, 1.0, v98
	v_sub_f32_e32 v99, 1.0, v99
	v_mul_f32_e32 v96, v96, v92
	v_mul_f32_e32 v97, v97, v93
	v_mul_f32_e32 v98, v98, v94
	v_mul_f32_e32 v99, v99, v95
	v_lshlrev_b32_e32 v92, 16, v58
	v_and_b32_e32 v93, 0xffff0000, v58
	v_lshlrev_b32_e32 v94, 16, v59
	v_and_b32_e32 v95, 0xffff0000, v59
	v_mul_f32_e32 v92, v92, v100
	v_mul_f32_e32 v93, v93, v101
	v_mul_f32_e32 v94, v94, v102
	v_mul_f32_e32 v95, v95, v103
	v_mov_b32_e32 v116, v96
	v_mov_b32_e32 v132, v97
	v_mov_b32_e32 v166, v98
	v_mov_b32_e32 v182, v99
	v_cvt_pk_bf16_f32 v92, v92, v93
	v_cvt_pk_bf16_f32 v93, v94, v95
	v_cvt_pk_bf16_f32 v96, v96, v97
	v_cvt_pk_bf16_f32 v97, v98, v99
	global_store_dwordx2 v112, v[92:93], s[2:3]
	global_store_dwordx2 v114, v[96:97], s[2:3]
	s_sub_u32 s2, s2, 0x400
	s_subb_u32 s3, s3, 0
	v_lshlrev_b32_e32 v92, 16, v60
	v_and_b32_e32 v93, 0xffff0000, v60
	v_lshlrev_b32_e32 v94, 16, v61
	v_and_b32_e32 v95, 0xffff0000, v61
	v_mul_f32_e32 v92, 0xbfb8aa3b, v92
	v_mul_f32_e32 v93, 0xbfb8aa3b, v93
	v_mul_f32_e32 v94, 0xbfb8aa3b, v94
; DEV u16 f2bf(float f) { return (u16)(pack2(f, f) & 0xffffu); }
; DEV float bf2f(u16 h) { return __uint_as_float(((unsigned)h) << 16); }
; DEV float sigmoid_f(float x) { return __builtin_amdgcn_rcpf(1.f + __expf(-x)); }
; DEV void phase_p15(const Params& p, int g) {
;     ...
;     P15_LOAD(0, 0);
;     P15_LOAD(1, 1);
; #pragma unroll
;     for (int j8 = 0; j8 < 8; ++j8) {
;       const int st = j8 % 3;
;       if (j8 < 6) { P15_LOAD((j8 + 2) % 3, j8 + 2); }
; #pragma unroll
;       for (int cc = 0; cc < 2; ++cc) {
;         const int c = tid + 256 * cc;
;         unsigned kb[8];
; #pragma unroll
;         for (int e = 0; e < 8; ++e) {
;           const int jj = j8 * 8 + e;
;           const int j = dir ? 63 - jj : jj;
;           const size_t tok = (size_t)cidx * 64 + j;
;           const float f = lb[cc] + (1.f - lb[cc]) * sigmoid_f(bf2f(xr[st][cc][e]));
;           G[cc] += __logf(f);
;           const float eg = __expf(G[cc]), ig = __expf(-G[cc]);
;           Qp[tok * 512 + c] = f2bf(bf2f(qr[st][cc][e]) * eg);
;           const u16 kk = f2bf((1.f - f) * ig);
;           Kp[tok * 512 + c] = kk;
;           kb[e] = kk;
;         }
;         const int s0 = dir ? 56 - 8 * j8 : 8 * j8;
;         uint4 w;
;         w.x = dir ? (kb[7] | (kb[6] << 16)) : (kb[0] | (kb[1] << 16));
;         w.y = dir ? (kb[5] | (kb[4] << 16)) : (kb[2] | (kb[3] << 16));
;         w.z = dir ? (kb[3] | (kb[2] << 16)) : (kb[4] | (kb[5] << 16));
;         w.w = dir ? (kb[1] | (kb[0] << 16)) : (kb[6] | (kb[7] << 16));
;         *(uint4*)(KT + (((size_t)cidx * 2 + dir) * 512 + c) * 64 + s0) = w;
;       }
	v_mul_f32_e32 v95, 0xbfb8aa3b, v95
	v_exp_f32_e32 v92, v92
	v_exp_f32_e32 v93, v93
	v_exp_f32_e32 v94, v94
	v_exp_f32_e32 v95, v95
	v_add_f32_e32 v92, 1.0, v92
	v_add_f32_e32 v93, 1.0, v93
	v_add_f32_e32 v94, 1.0, v94
	v_add_f32_e32 v95, 1.0, v95
	v_rcp_f32_e32 v92, v92
	v_rcp_f32_e32 v93, v93
	v_rcp_f32_e32 v94, v94
	v_rcp_f32_e32 v95, v95
	v_fma_f32 v96, v72, v92, v68
	v_fma_f32 v97, v73, v93, v69
	v_fma_f32 v98, v74, v94, v70
	v_fma_f32 v99, v75, v95, v71
	v_cmp_gt_f32_e64 s[22:23], s30, v96
	v_cmp_gt_f32_e64 s[24:25], s30, v97
	v_cmp_gt_f32_e64 s[26:27], s30, v98
	v_cmp_gt_f32_e64 s[28:29], s30, v99
	v_cndmask_b32_e64 v92, 0, 32, s[22:23]
	v_cndmask_b32_e64 v93, 0, 32, s[24:25]
	v_cndmask_b32_e64 v94, 0, 32, s[26:27]
	v_cndmask_b32_e64 v95, 0, 32, s[28:29]
	v_ldexp_f32 v92, v96, v92
	v_ldexp_f32 v93, v97, v93
	v_ldexp_f32 v94, v98, v94
	v_ldexp_f32 v95, v99, v95
	v_log_f32_e32 v92, v92
	v_log_f32_e32 v93, v93
	v_log_f32_e32 v94, v94
	v_log_f32_e32 v95, v95
	v_mul_f32_e32 v100, 0x3f317217, v92
	v_mul_f32_e32 v101, 0x3f317217, v93
	v_mul_f32_e32 v102, 0x3f317217, v94
	v_mul_f32_e32 v103, 0x3f317217, v95
	v_fma_f32 v100, v92, s31, -v100
	v_fma_f32 v101, v93, s31, -v101
	v_fma_f32 v102, v94, s31, -v102
	v_fma_f32 v103, v95, s31, -v103
	v_fmac_f32_e32 v100, 0x3377d1cf, v92
	v_fmac_f32_e32 v101, 0x3377d1cf, v93
	v_fmac_f32_e32 v102, 0x3377d1cf, v94
	v_fmac_f32_e32 v103, 0x3377d1cf, v95
	v_fmac_f32_e32 v100, 0x3f317217, v92
	v_fmac_f32_e32 v101, 0x3f317217, v93
	v_fmac_f32_e32 v102, 0x3f317217, v94
	v_fmac_f32_e32 v103, 0x3f317217, v95
	v_cmp_lt_f32_e64 vcc, |v92|, s34
	v_cndmask_b32_e32 v92, v92, v100, vcc
	v_cmp_lt_f32_e64 vcc, |v93|, s34
	v_cndmask_b32_e32 v93, v93, v101, vcc
	v_cmp_lt_f32_e64 vcc, |v94|, s34
	v_cndmask_b32_e32 v94, v94, v102, vcc
	v_cmp_lt_f32_e64 vcc, |v95|, s34
	v_cndmask_b32_e32 v95, v95, v103, vcc
	v_cndmask_b32_e64 v100, 0, v213, s[22:23]
	v_cndmask_b32_e64 v101, 0, v213, s[24:25]
	v_cndmask_b32_e64 v102, 0, v213, s[26:27]
	v_cndmask_b32_e64 v103, 0, v213, s[28:29]
	v_sub_f32_e32 v92, v92, v100
	v_sub_f32_e32 v93, v93, v101
	v_sub_f32_e32 v94, v94, v102
	v_sub_f32_e32 v95, v95, v103
	v_add_f32_e32 v64, v64, v92
	v_add_f32_e32 v65, v65, v93
	v_add_f32_e32 v66, v66, v94
	v_add_f32_e32 v67, v67, v95
	v_mul_f32_e32 v92, 0xbfb8aa3b, v64
	v_mul_f32_e32 v93, 0xbfb8aa3b, v65
	v_mul_f32_e32 v94, 0xbfb8aa3b, v66
	v_mul_f32_e32 v95, 0xbfb8aa3b, v67
	v_mul_f32_e32 v100, 0x3fb8aa3b, v64
	v_mul_f32_e32 v101, 0x3fb8aa3b, v65
	v_mul_f32_e32 v102, 0x3fb8aa3b, v66
	v_mul_f32_e32 v103, 0x3fb8aa3b, v67
	v_exp_f32_e32 v92, v92
	v_exp_f32_e32 v93, v93
	v_exp_f32_e32 v94, v94
	v_exp_f32_e32 v95, v95
	v_exp_f32_e32 v100, v100
	v_exp_f32_e32 v101, v101
	v_exp_f32_e32 v102, v102
	v_exp_f32_e32 v103, v103
	v_sub_f32_e32 v96, 1.0, v96
	v_sub_f32_e32 v97, 1.0, v97
	v_sub_f32_e32 v98, 1.0, v98
	v_sub_f32_e32 v99, 1.0, v99
	v_mul_f32_e32 v96, v96, v92
	v_mul_f32_e32 v97, v97, v93
	v_mul_f32_e32 v98, v98, v94
	v_mul_f32_e32 v99, v99, v95
	v_lshlrev_b32_e32 v92, 16, v62
	v_and_b32_e32 v93, 0xffff0000, v62
	v_lshlrev_b32_e32 v94, 16, v63
	v_and_b32_e32 v95, 0xffff0000, v63
	v_mul_f32_e32 v92, v92, v100
	v_mul_f32_e32 v93, v93, v101
	v_mul_f32_e32 v94, v94, v102
	v_mul_f32_e32 v95, v95, v103
	v_cvt_pk_bf16_f32 v116, v96, v116
	v_cvt_pk_bf16_f32 v132, v97, v132
	v_cvt_pk_bf16_f32 v166, v98, v166
	v_cvt_pk_bf16_f32 v182, v99, v182
	v_cvt_pk_bf16_f32 v92, v92, v93
	v_cvt_pk_bf16_f32 v93, v94, v95
	v_cvt_pk_bf16_f32 v96, v96, v97
	v_cvt_pk_bf16_f32 v97, v98, v99
	global_store_dwordx2 v112, v[92:93], s[2:3]
	global_store_dwordx2 v114, v[96:97], s[2:3]
	s_sub_u32 s2, s2, 0x400
	s_subb_u32 s3, s3, 0
	s_cmp_eq_u32 s35, 1
	s_cbranch_scc1 .Lp15_d1_nl3
	global_load_dwordx2 v[32:33], v113, s[0:1]
	global_load_dwordx2 v[34:35], v112, s[0:1]
	s_sub_u32 s0, s0, 0x1400
	s_subb_u32 s1, s1, 0
	global_load_dwordx2 v[36:37], v113, s[0:1]
	global_load_dwordx2 v[38:39], v112, s[0:1]
	s_sub_u32 s0, s0, 0x1400
	s_subb_u32 s1, s1, 0
	global_load_dwordx2 v[40:41], v113, s[0:1]
	global_load_dwordx2 v[42:43], v112, s[0:1]
	s_sub_u32 s0, s0, 0x1400
	s_subb_u32 s1, s1, 0
	global_load_dwordx2 v[44:45], v113, s[0:1]
	global_load_dwordx2 v[46:47], v112, s[0:1]
	s_sub_u32 s0, s0, 0x1400
	s_subb_u32 s1, s1, 0
	global_load_dwordx2 v[48:49], v113, s[0:1]
	global_load_dwordx2 v[50:51], v112, s[0:1]
	s_sub_u32 s0, s0, 0x1400
	s_subb_u32 s1, s1, 0
	global_load_dwordx2 v[52:53], v113, s[0:1]
	global_load_dwordx2 v[54:55], v112, s[0:1]
	s_sub_u32 s0, s0, 0x1400
	s_subb_u32 s1, s1, 0
	global_load_dwordx2 v[56:57], v113, s[0:1]
	global_load_dwordx2 v[58:59], v112, s[0:1]
	s_sub_u32 s0, s0, 0x1400
	s_subb_u32 s1, s1, 0
	global_load_dwordx2 v[60:61], v113, s[0:1]
	global_load_dwordx2 v[62:63], v112, s[0:1]
	s_sub_u32 s0, s0, 0x1400
	s_subb_u32 s1, s1, 0
